# full-line stores (8 rows x 128B via DPP exchange + permuted Bt rows) in up-proj epilogues (phases 6,12) on top of best stack
# speedup vs baseline: 1.0020x; 1.0020x over previous
; __device__ __forceinline__ u16 f2bf(float f) { unsigned u = __float_as_uint(f); u += 0x7FFFu + ((u >> 16) & 1u); return (u16)(u >> 16); }
; __device__ __forceinline__ void transpose_job(const float* W, int K, int N, int Npad, u16* dst, const float* gain, u16* tile) {
;     ...
;         for (int tt = 0; tt < 2; ++tt)
; #pragma unroll
;             for (int i = 0; i < 2; ++i) { const int k = (tid >> 4) + 32 * i, n4 = (tid & 15) * 4;
; #pragma unroll
;                 for (int j = 0; j < 4; ++j) tile[tt * 64 * 72 + (n4 + j) * 72 + k] = f2bf(v[tt][i][j] * gk[tt][i]); }
;         __syncthreads();
; #pragma unroll
;         for (int tt = 0; tt < 2; ++tt) { const int t = t0 + tt * gridDim.x;
;             if (t < ntiles) { const int k0 = (t % kt) * 64, n0 = (t / kt) * 64; const int n = tid >> 3, k8 = (tid & 7) * 8;
;                 const u32x4 w = *(const u32x4*)(tile + tt * 64 * 72 + n * 72 + k8); *(u32x4*)(dst + (size_t)(n0 + n) * K + k0 + k8) = w; } }
.LBB0_90:
	s_waitcnt vmcnt(0)
	v_mul_f32_e32 v2, v2, v24
	v_bfe_u32 v23, v2, 16, 1
	v_add3_u32 v2, v2, v23, s23
	ds_write_b16_d16_hi v29, v2
	v_mul_f32_e32 v2, v3, v24
	v_bfe_u32 v3, v2, 16, 1
	v_add3_u32 v2, v2, v3, s23
	ds_write_b16_d16_hi v29, v2 offset:144
	v_mul_f32_e32 v2, v4, v24
	v_bfe_u32 v3, v2, 16, 1
	v_add3_u32 v2, v2, v3, s23
	ds_write_b16_d16_hi v29, v2 offset:288
	v_mul_f32_e32 v2, v5, v24
	v_bfe_u32 v3, v2, 16, 1
	v_add3_u32 v2, v2, v3, s23
	ds_write_b16_d16_hi v29, v2 offset:432
	v_mul_f32_e32 v2, v6, v25
	v_bfe_u32 v3, v2, 16, 1
	v_add3_u32 v2, v2, v3, s23
	ds_write_b16_d16_hi v29, v2 offset:64
	v_mul_f32_e32 v2, v7, v25
	v_bfe_u32 v3, v2, 16, 1
	v_add3_u32 v2, v2, v3, s23
	ds_write_b16_d16_hi v29, v2 offset:208
	v_mul_f32_e32 v2, v8, v25
	v_bfe_u32 v3, v2, 16, 1
	v_add3_u32 v2, v2, v3, s23
	ds_write_b16_d16_hi v29, v2 offset:352
	v_mul_f32_e32 v2, v9, v25
	v_bfe_u32 v3, v2, 16, 1
	v_add3_u32 v2, v2, v3, s23
	ds_write_b16_d16_hi v29, v2 offset:496
	v_mul_f32_e32 v2, v10, v30
	v_bfe_u32 v3, v2, 16, 1
	v_add3_u32 v2, v2, v3, s23
	ds_write_b16_d16_hi v29, v2 offset:9216
	v_mul_f32_e32 v2, v11, v30
	v_bfe_u32 v3, v2, 16, 1
	v_add3_u32 v2, v2, v3, s23
	ds_write_b16_d16_hi v29, v2 offset:9360
	v_mul_f32_e32 v2, v12, v30
	v_bfe_u32 v3, v2, 16, 1
	v_add3_u32 v2, v2, v3, s23
	ds_write_b16_d16_hi v29, v2 offset:9504
	v_mul_f32_e32 v2, v13, v30
	v_bfe_u32 v3, v2, 16, 1
	v_add3_u32 v2, v2, v3, s23
	ds_write_b16_d16_hi v29, v2 offset:9648
	v_mul_f32_e32 v2, v14, v22
	v_bfe_u32 v3, v2, 16, 1
	v_add3_u32 v2, v2, v3, s23
	ds_write_b16_d16_hi v29, v2 offset:9280
	v_mul_f32_e32 v2, v15, v22
	v_bfe_u32 v3, v2, 16, 1
	v_add3_u32 v2, v2, v3, s23
	ds_write_b16_d16_hi v29, v2 offset:9424
	v_mul_f32_e32 v2, v16, v22
	v_bfe_u32 v3, v2, 16, 1
	v_add3_u32 v2, v2, v3, s23
	ds_write_b16_d16_hi v29, v2 offset:9568
	v_mul_f32_e32 v2, v17, v22
	v_bfe_u32 v3, v2, 16, 1
	v_add3_u32 v2, v2, v3, s23
	v_add_u32_e32 v6, s26, v26
	ds_write_b16_d16_hi v29, v2 offset:9712
	s_waitcnt lgkmcnt(0)
	s_barrier
	ds_read_b128 v[2:5], v27
	v_bfe_u32 v200, v6, 6, 2
	v_bfe_u32 v201, v6, 5, 1
	v_and_b32_e32 v6, 0xffffff1f, v6
	v_lshl_or_b32 v6, v200, 5, v6
	v_lshl_or_b32 v6, v201, 7, v6
	v_ashrrev_i32_e32 v7, 31, v6
	v_lshlrev_b64 v[6:7], 11, v[6:7]
	v_lshl_add_u64 v[6:7], s[8:9], 0, v[6:7]
	s_ashr_i32 s11, s10, 31
	v_lshl_add_u64 v[6:7], s[10:11], 1, v[6:7]
	v_lshl_add_u64 v[6:7], v[6:7], 0, v[20:21]
	s_and_b64 vcc, exec, s[2:3]
	s_waitcnt lgkmcnt(0)
	global_store_dwordx4 v[6:7], v[2:5], off
	s_cbranch_vccnz .LBB0_65
	s_ashr_i32 s2, s27, 31
	s_lshr_b32 s2, s2, 28
	s_add_i32 s3, s27, s2
	s_and_b32 s2, s3, 0x3fffff0
	s_lshl_b32 s3, s3, 2
	s_andn2_b32 s3, s3, 63
	v_add_u32_e32 v6, s3, v26
	s_sub_i32 s2, s27, s2
	ds_read_b128 v[2:5], v27 offset:9216
	v_bfe_u32 v200, v6, 6, 2
	v_bfe_u32 v201, v6, 5, 1
	v_and_b32_e32 v6, 0xffffff1f, v6
	v_lshl_or_b32 v6, v200, 5, v6
	v_lshl_or_b32 v6, v201, 7, v6
	v_ashrrev_i32_e32 v7, 31, v6
	s_lshl_b32 s2, s2, 6
	v_lshlrev_b64 v[6:7], 11, v[6:7]
	v_lshl_add_u64 v[6:7], s[8:9], 0, v[6:7]
	s_ashr_i32 s3, s2, 31
	v_lshl_add_u64 v[6:7], s[2:3], 1, v[6:7]
	v_lshl_add_u64 v[6:7], v[6:7], 0, v[20:21]
	s_waitcnt lgkmcnt(0)
	global_store_dwordx4 v[6:7], v[2:5], off
	s_branch .LBB0_65

; __device__ __forceinline__ u16 f2bf(float f) { unsigned u = __float_as_uint(f); u += 0x7FFFu + ((u >> 16) & 1u); return (u16)(u >> 16); }
; __device__ __forceinline__ void transpose_job(const float* W, int K, int N, int Npad, u16* dst, const float* gain, u16* tile) {
;     ...
;             for (int i = 0; i < 2; ++i) { const int k = (tid >> 4) + 32 * i, n = n0 + (tid & 15) * 4;
;                 v[tt][i] = (f32x4){0.f, 0.f, 0.f, 0.f}; if (ok && n < N) v[tt][i] = *(const f32x4*)(W + (size_t)(k0 + k) * N + n);
;                 gk[tt][i] = gain ? gain[k0 + k] : 1.0f; } }
; #pragma unroll
;         for (int tt = 0; tt < 2; ++tt)
; #pragma unroll
;             for (int i = 0; i < 2; ++i) { const int k = (tid >> 4) + 32 * i, n4 = (tid & 15) * 4;
; #pragma unroll
;                 for (int j = 0; j < 4; ++j) tile[tt * 64 * 72 + (n4 + j) * 72 + k] = f2bf(v[tt][i][j] * gk[tt][i]); }
;         __syncthreads();
; #pragma unroll
;         for (int tt = 0; tt < 2; ++tt) { const int t = t0 + tt * gridDim.x;
;             if (t < ntiles) { const int k0 = (t % kt) * 64, n0 = (t / kt) * 64; const int n = tid >> 3, k8 = (tid & 7) * 8;
;                 const u32x4 w = *(const u32x4*)(tile + tt * 64 * 72 + n * 72 + k8); *(u32x4*)(dst + (size_t)(n0 + n) * K + k0 + k8) = w; } }
.LBB0_106:
	s_or_b64 exec, exec, s[14:15]
	v_lshl_add_u64 v[22:23], v[24:25], 2, s[10:11]
	global_load_dword v22, v[22:23], off
	s_waitcnt vmcnt(3)
	v_mul_f32_e32 v23, v2, v19
	v_mul_f32_e32 v4, v4, v19
	v_mul_f32_e32 v5, v5, v19
	v_mul_f32_e32 v24, v3, v19
	s_waitcnt vmcnt(2)
	v_mul_f32_e32 v10, v10, v30
	v_mul_f32_e32 v11, v11, v30
	v_mul_f32_e32 v12, v12, v30
	v_mul_f32_e32 v13, v13, v30
	s_waitcnt vmcnt(1)
	v_mul_f32_e32 v14, v14, v31
	v_mul_f32_e32 v15, v15, v31
	v_mul_f32_e32 v16, v16, v31
	v_mul_f32_e32 v17, v17, v31
	v_add_u32_e32 v2, s25, v26
	v_bfe_u32 v19, v23, 16, 1
	v_bfe_u32 v30, v4, 16, 1
	v_bfe_u32 v31, v5, 16, 1
	v_bfe_u32 v25, v24, 16, 1
	v_bfe_u32 v32, v10, 16, 1
	v_bfe_u32 v33, v11, 16, 1
	v_bfe_u32 v34, v12, 16, 1
	v_bfe_u32 v35, v13, 16, 1
	v_bfe_u32 v36, v14, 16, 1
	v_bfe_u32 v37, v15, 16, 1
	v_bfe_u32 v38, v16, 16, 1
	v_bfe_u32 v39, v17, 16, 1
	v_bfe_u32 v200, v2, 6, 2
	v_bfe_u32 v201, v2, 5, 1
	v_and_b32_e32 v2, 0xffffff1f, v2
	v_lshl_or_b32 v2, v200, 5, v2
	v_lshl_or_b32 v2, v201, 7, v2
	v_ashrrev_i32_e32 v3, 31, v2
	v_add3_u32 v19, v23, v19, s17
	v_add3_u32 v4, v4, v30, s17
	v_add3_u32 v5, v5, v31, s17
	v_add3_u32 v23, v24, v25, s17
	v_add3_u32 v24, v10, v32, s17
	v_add3_u32 v25, v11, v33, s17
	v_add3_u32 v12, v12, v34, s17
	v_add3_u32 v13, v13, v35, s17
	v_add3_u32 v14, v14, v36, s17
	v_add3_u32 v15, v15, v37, s17
	v_add3_u32 v16, v16, v38, s17
	v_add3_u32 v17, v17, v39, s17
	v_lshlrev_b64 v[10:11], 11, v[2:3]
	ds_write_b16_d16_hi v29, v19
	ds_write_b16_d16_hi v29, v23 offset:144
	ds_write_b16_d16_hi v29, v4 offset:288
	ds_write_b16_d16_hi v29, v5 offset:432
	ds_write_b16_d16_hi v29, v24 offset:64
	ds_write_b16_d16_hi v29, v25 offset:208
	ds_write_b16_d16_hi v29, v12 offset:352
	ds_write_b16_d16_hi v29, v13 offset:496
	ds_write_b16_d16_hi v29, v14 offset:9216
	ds_write_b16_d16_hi v29, v15 offset:9360
	ds_write_b16_d16_hi v29, v16 offset:9504
	ds_write_b16_d16_hi v29, v17 offset:9648
	s_sub_i32 s12, 0, s26
	s_add_i32 s12, s22, s12
	s_ashr_i32 s13, s12, 31
	s_and_b64 vcc, exec, s[0:1]
	s_waitcnt vmcnt(0)
	v_mul_f32_e32 v2, v6, v22
	v_mul_f32_e32 v3, v7, v22
	v_mul_f32_e32 v4, v8, v22
	v_mul_f32_e32 v5, v9, v22
	v_bfe_u32 v6, v2, 16, 1
	v_bfe_u32 v7, v3, 16, 1
	v_bfe_u32 v8, v4, 16, 1
	v_bfe_u32 v9, v5, 16, 1
	v_add3_u32 v2, v2, v6, s17
	v_add3_u32 v3, v3, v7, s17
	v_add3_u32 v4, v4, v8, s17
	v_add3_u32 v5, v5, v9, s17
	ds_write_b16_d16_hi v29, v2 offset:9280
	ds_write_b16_d16_hi v29, v3 offset:9424
	ds_write_b16_d16_hi v29, v4 offset:9568
	ds_write_b16_d16_hi v29, v5 offset:9712
	s_waitcnt lgkmcnt(0)
	s_barrier
	ds_read_b128 v[2:5], v27
	v_lshl_add_u64 v[6:7], s[8:9], 0, v[10:11]
	v_lshl_add_u64 v[6:7], s[12:13], 1, v[6:7]
	v_lshl_add_u64 v[6:7], v[6:7], 0, v[20:21]
	s_waitcnt lgkmcnt(0)
	global_store_dwordx4 v[6:7], v[2:5], off
	s_cbranch_vccnz .LBB0_93
	s_ashr_i32 s0, s24, 31
	s_lshr_b32 s0, s0, 28
	s_add_i32 s1, s24, s0
	s_and_b32 s0, s1, 0x3fffff0
	s_lshl_b32 s1, s1, 2
	s_andn2_b32 s1, s1, 63
	v_add_u32_e32 v6, s1, v26
	s_sub_i32 s0, s24, s0
	ds_read_b128 v[2:5], v27 offset:9216
	v_bfe_u32 v200, v6, 6, 2
	v_bfe_u32 v201, v6, 5, 1
	v_and_b32_e32 v6, 0xffffff1f, v6
	v_lshl_or_b32 v6, v200, 5, v6
	v_lshl_or_b32 v6, v201, 7, v6
	v_ashrrev_i32_e32 v7, 31, v6
	s_lshl_b32 s0, s0, 6
	v_lshlrev_b64 v[6:7], 11, v[6:7]
	v_lshl_add_u64 v[6:7], s[8:9], 0, v[6:7]
	s_ashr_i32 s1, s0, 31
	v_lshl_add_u64 v[6:7], s[0:1], 1, v[6:7]
	v_lshl_add_u64 v[6:7], v[6:7], 0, v[20:21]
	s_waitcnt lgkmcnt(0)
	global_store_dwordx4 v[6:7], v[2:5], off
	s_branch .LBB0_93

; #define PG8_STAGE(bufoff, gbase, voff) do { _Pragma("unroll") for (int _i = 0; _i < 2; ++_i) \
;         __builtin_amdgcn_global_load_lds((const unsigned*)((const char*)(gbase) + (voff)[_i]), (LAS unsigned*)(lds + (bufoff) + ldsw + _i * 8192), 16, 0, 0); } while (0)
; #define PG8_LDA(dst, b, h) do { _Pragma("unroll") for (int m = 0; m < 4; ++m) _Pragma("unroll") for (int k = 0; k < 2; ++k) dst[m][k] = *(const LAS bf16x8*)(lds + PG8_SA(b, h) + aoff + m * 2048 + k * 1024); } while (0)
; #define PG8_LDB(dst, b, h) do { _Pragma("unroll") for (int n = 0; n < 2; ++n) _Pragma("unroll") for (int k = 0; k < 2; ++k) dst[n][k] = *(const LAS bf16x8*)(lds + PG8_SB(b, h) + boff + n * 2048 + k * 1024); } while (0)
; #define PG8_MMA(ai, bj, At, Bt) do { __builtin_amdgcn_s_setprio(1); _Pragma("unroll") for (int m = 0; m < 4; ++m) _Pragma("unroll") for (int n = 0; n < 2; ++n) _Pragma("unroll") for (int k = 0; k < 2; ++k) \
;         acc[ai][bj][m][n] = __builtin_amdgcn_mfma_f32_16x16x32_bf16(Bt[n][k], At[m][k], acc[ai][bj][m][n], 0, 0, 0); __builtin_amdgcn_s_setprio(0); } while (0)
; #define PG8_WAIT_V(n) asm volatile("s_waitcnt vmcnt(" #n ")" ::: "memory")
; #define PG8_WAIT_L(n) asm volatile("s_waitcnt lgkmcnt(" #n ")" ::: "memory")
; #define PG8_BAR __builtin_amdgcn_s_barrier()
; #define PG8_SCHED __builtin_amdgcn_sched_barrier(0)
; template <class Epi>
; __device__ __forceinline__ void gemm_phase(LAS unsigned char* lds, const Gemm g, const StaticOrder& S, const Epi& E) {
;     ...
;             PG8_LDB(B0, 0, 0); PG8_SCHED; PG8_LDA(At, 0, 0); PG8_STAGE(PG8_SA(1, 1), a1 + hstepA, voffA);
;             PG8_WAIT_L(8); PG8_BAR; PG8_WAIT_L(0); PG8_MMA(0, 0, At, B0); PG8_BAR; PG8_SCHED;
;             PG8_LDB(B1, 0, 1); PG8_STAGE(PG8_SB(0, 0), b2, voffB);
;             PG8_BAR; PG8_WAIT_L(0); PG8_MMA(0, 1, At, B1); PG8_BAR;
;             PG8_LDA(At, 0, 1); PG8_STAGE(PG8_SA(0, 0), a2, voffA);
;             PG8_BAR; PG8_WAIT_L(0); PG8_MMA(1, 0, At, B0); PG8_BAR; PG8_SCHED;
;             PG8_STAGE(PG8_SB(0, 1), b2 + hstepB, voffB);
;             PG8_WAIT_V(6); PG8_BAR; PG8_MMA(1, 1, At, B1); PG8_BAR;
.LBB0_770:
	ds_read_b128 v[146:149], v177
	ds_read_b128 v[154:157], v177 offset:1024
	ds_read_b128 v[158:161], v177 offset:2048
	ds_read_b128 v[162:165], v177 offset:3072
	s_add_u32 s22, s20, 0xfffc0080
	s_addc_u32 s23, s21, -1
	s_cmp_eq_u32 s45, 12
	s_cselect_b32 s25, s13, s23
	s_cselect_b32 s24, s41, s22
	s_cselect_b32 s23, s11, s44
	s_cselect_b32 s22, s42, s43
	v_lshl_add_u64 v[150:151], s[20:21], 0, v[138:139]
	s_add_i32 m0, s19, 0xc000
	ds_read_b128 v[166:169], v178
	ds_read_b128 v[170:173], v178 offset:1024
	ds_read_b128 v[182:185], v178 offset:2048
	ds_read_b128 v[186:189], v178 offset:3072
	ds_read_b128 v[190:193], v178 offset:4096
	ds_read_b128 v[194:197], v178 offset:5120
	ds_read_b128 v[198:201], v178 offset:6144
	ds_read_b128 v[202:205], v178 offset:7168
	global_load_lds_dwordx4 v[150:151], off
	v_lshl_add_u64 v[150:151], s[20:21], 0, v[140:141]
	s_add_i32 m0, s19, 0xe000
	s_nop 0
	global_load_lds_dwordx4 v[150:151], off
	s_waitcnt lgkmcnt(8)
	s_barrier
	s_waitcnt lgkmcnt(0)
	s_setprio 1
	s_waitcnt lgkmcnt(0)
	v_mfma_f32_16x16x32_bf16 v[124:127], v[146:149], v[166:169], v[124:127]
	v_mfma_f32_16x16x32_bf16 v[120:123], v[158:161], v[166:169], v[120:123]
	v_mfma_f32_16x16x32_bf16 v[108:111], v[146:149], v[182:185], v[108:111]
	v_mfma_f32_16x16x32_bf16 v[104:107], v[158:161], v[182:185], v[104:107]
	v_mfma_f32_16x16x32_bf16 v[92:95], v[146:149], v[190:193], v[92:95]
	v_mfma_f32_16x16x32_bf16 v[88:91], v[158:161], v[190:193], v[88:91]
	v_mfma_f32_16x16x32_bf16 v[76:79], v[146:149], v[198:201], v[76:79]
	v_mfma_f32_16x16x32_bf16 v[72:75], v[158:161], v[198:201], v[72:75]
	v_mfma_f32_16x16x32_bf16 v[124:127], v[154:157], v[170:173], v[124:127]
	v_mfma_f32_16x16x32_bf16 v[120:123], v[162:165], v[170:173], v[120:123]
	v_mfma_f32_16x16x32_bf16 v[108:111], v[154:157], v[186:189], v[108:111]
	v_mfma_f32_16x16x32_bf16 v[104:107], v[162:165], v[186:189], v[104:107]
	v_mfma_f32_16x16x32_bf16 v[92:95], v[154:157], v[194:197], v[92:95]
	v_mfma_f32_16x16x32_bf16 v[88:91], v[162:165], v[194:197], v[88:91]
	v_mfma_f32_16x16x32_bf16 v[76:79], v[154:157], v[202:205], v[76:79]
	v_mfma_f32_16x16x32_bf16 v[72:75], v[162:165], v[202:205], v[72:75]
	s_setprio 0
	s_barrier
	s_add_i32 s46, s7, s29
	v_lshl_add_u64 v[150:151], s[22:23], 0, v[130:131]
	s_mov_b32 m0, s46
	ds_read_b128 v[206:209], v179
	ds_read_b128 v[210:213], v179 offset:1024
	ds_read_b128 v[214:217], v179 offset:2048
	ds_read_b128 v[218:221], v179 offset:3072
	global_load_lds_dwordx4 v[150:151], off
	v_lshl_add_u64 v[222:223], s[22:23], 0, v[134:135]
	s_add_i32 m0, s46, 0x2000
	s_nop 0
	global_load_lds_dwordx4 v[222:223], off
	s_barrier
	s_waitcnt lgkmcnt(0)
	s_setprio 1
	s_waitcnt lgkmcnt(0)
	v_mfma_f32_16x16x32_bf16 v[116:119], v[206:209], v[166:169], v[116:119]
	v_mfma_f32_16x16x32_bf16 v[112:115], v[214:217], v[166:169], v[112:115]
	v_mfma_f32_16x16x32_bf16 v[100:103], v[206:209], v[182:185], v[100:103]
	v_mfma_f32_16x16x32_bf16 v[96:99], v[214:217], v[182:185], v[96:99]
	v_mfma_f32_16x16x32_bf16 v[84:87], v[206:209], v[190:193], v[84:87]
	v_mfma_f32_16x16x32_bf16 v[80:83], v[214:217], v[190:193], v[80:83]
	v_mfma_f32_16x16x32_bf16 v[68:71], v[206:209], v[198:201], v[68:71]
	v_mfma_f32_16x16x32_bf16 v[64:67], v[214:217], v[198:201], v[64:67]
	v_mfma_f32_16x16x32_bf16 v[116:119], v[210:213], v[170:173], v[116:119]
	v_mfma_f32_16x16x32_bf16 v[112:115], v[218:221], v[170:173], v[112:115]
	v_mfma_f32_16x16x32_bf16 v[100:103], v[210:213], v[186:189], v[100:103]
	v_mfma_f32_16x16x32_bf16 v[96:99], v[218:221], v[186:189], v[96:99]
	v_mfma_f32_16x16x32_bf16 v[84:87], v[210:213], v[194:197], v[84:87]
	v_mfma_f32_16x16x32_bf16 v[80:83], v[218:221], v[194:197], v[80:83]
	v_mfma_f32_16x16x32_bf16 v[68:71], v[210:213], v[202:205], v[68:71]
	v_mfma_f32_16x16x32_bf16 v[64:67], v[218:221], v[202:205], v[64:67]
	s_setprio 0
	s_mov_b32 m0, s19
	v_lshl_add_u64 v[224:225], s[24:25], 0, v[128:129]
	s_barrier
	ds_read_b128 v[166:169], v178 offset:16384
	ds_read_b128 v[170:173], v178 offset:17408
	ds_read_b128 v[182:185], v178 offset:18432
	ds_read_b128 v[186:189], v178 offset:19456
	ds_read_b128 v[190:193], v178 offset:20480
	ds_read_b128 v[194:197], v178 offset:21504
	ds_read_b128 v[198:201], v178 offset:22528
	ds_read_b128 v[202:205], v178 offset:23552
	global_load_lds_dwordx4 v[224:225], off
	v_lshl_add_u64 v[226:227], s[24:25], 0, v[132:133]
	s_mov_b32 m0, s30
	s_nop 0
	global_load_lds_dwordx4 v[226:227], off
	s_barrier
	s_waitcnt lgkmcnt(0)
	s_setprio 1
	s_waitcnt lgkmcnt(0)
	v_mfma_f32_16x16x32_bf16 v[60:63], v[146:149], v[166:169], v[60:63]
	v_mfma_f32_16x16x32_bf16 v[56:59], v[158:161], v[166:169], v[56:59]
	v_mfma_f32_16x16x32_bf16 v[44:47], v[146:149], v[182:185], v[44:47]
	v_mfma_f32_16x16x32_bf16 v[40:43], v[158:161], v[182:185], v[40:43]
	v_mfma_f32_16x16x32_bf16 v[28:31], v[146:149], v[190:193], v[28:31]
	v_mfma_f32_16x16x32_bf16 v[24:27], v[158:161], v[190:193], v[24:27]
	v_mfma_f32_16x16x32_bf16 v[12:15], v[146:149], v[198:201], v[12:15]
	v_mfma_f32_16x16x32_bf16 v[8:11], v[158:161], v[198:201], v[8:11]
	v_mfma_f32_16x16x32_bf16 v[60:63], v[154:157], v[170:173], v[60:63]
	v_mfma_f32_16x16x32_bf16 v[56:59], v[162:165], v[170:173], v[56:59]
	v_mfma_f32_16x16x32_bf16 v[44:47], v[154:157], v[186:189], v[44:47]
	v_mfma_f32_16x16x32_bf16 v[40:43], v[162:165], v[186:189], v[40:43]
	v_mfma_f32_16x16x32_bf16 v[28:31], v[154:157], v[194:197], v[28:31]
	v_mfma_f32_16x16x32_bf16 v[24:27], v[162:165], v[194:197], v[24:27]
	v_mfma_f32_16x16x32_bf16 v[12:15], v[154:157], v[202:205], v[12:15]
	v_mfma_f32_16x16x32_bf16 v[8:11], v[162:165], v[202:205], v[8:11]
	s_setprio 0
	s_barrier
; #define PG8_STAGE(bufoff, gbase, voff) do { _Pragma("unroll") for (int _i = 0; _i < 2; ++_i) \
;         __builtin_amdgcn_global_load_lds((const unsigned*)((const char*)(gbase) + (voff)[_i]), (LAS unsigned*)(lds + (bufoff) + ldsw + _i * 8192), 16, 0, 0); } while (0)
; #define PG8_LDA(dst, b, h) do { _Pragma("unroll") for (int m = 0; m < 4; ++m) _Pragma("unroll") for (int k = 0; k < 2; ++k) dst[m][k] = *(const LAS bf16x8*)(lds + PG8_SA(b, h) + aoff + m * 2048 + k * 1024); } while (0)
; #define PG8_LDB(dst, b, h) do { _Pragma("unroll") for (int n = 0; n < 2; ++n) _Pragma("unroll") for (int k = 0; k < 2; ++k) dst[n][k] = *(const LAS bf16x8*)(lds + PG8_SB(b, h) + boff + n * 2048 + k * 1024); } while (0)
; #define PG8_MMA(ai, bj, At, Bt) do { __builtin_amdgcn_s_setprio(1); _Pragma("unroll") for (int m = 0; m < 4; ++m) _Pragma("unroll") for (int n = 0; n < 2; ++n) _Pragma("unroll") for (int k = 0; k < 2; ++k) \
;         acc[ai][bj][m][n] = __builtin_amdgcn_mfma_f32_16x16x32_bf16(Bt[n][k], At[m][k], acc[ai][bj][m][n], 0, 0, 0); __builtin_amdgcn_s_setprio(0); } while (0)
; #define PG8_WAIT_V(n) asm volatile("s_waitcnt vmcnt(" #n ")" ::: "memory")
; #define PG8_WAIT_L(n) asm volatile("s_waitcnt lgkmcnt(" #n ")" ::: "memory")
; #define PG8_BAR __builtin_amdgcn_s_barrier()
; #define PG8_SCHED __builtin_amdgcn_sched_barrier(0)
; template <class Epi>
; __device__ __forceinline__ void gemm_phase(LAS unsigned char* lds, const Gemm g, const StaticOrder& S, const Epi& E) {
;     ...
;             PG8_WAIT_V(6); PG8_BAR; PG8_MMA(1, 1, At, B1); PG8_BAR;
;             PG8_LDB(B0, 1, 0); PG8_SCHED; PG8_LDA(At, 1, 0); PG8_STAGE(PG8_SA(0, 1), a2 + hstepA, voffA);
;             PG8_WAIT_L(8); PG8_BAR; PG8_WAIT_L(0); PG8_MMA(0, 0, At, B0); PG8_BAR; PG8_SCHED;
;             PG8_LDB(B1, 1, 1); PG8_STAGE(PG8_SB(1, 0), b3, voffB);
;             PG8_BAR; PG8_WAIT_L(0); PG8_MMA(0, 1, At, B1); PG8_BAR;
;             PG8_LDA(At, 1, 1); PG8_STAGE(PG8_SA(1, 0), a3, voffA);
;             PG8_BAR; PG8_WAIT_L(0); PG8_MMA(1, 0, At, B0); PG8_BAR; PG8_SCHED;
	s_add_u32 s46, s22, 0x40000
	s_addc_u32 s47, s23, 0
	s_add_i32 s48, s38, s29
	v_lshl_add_u64 v[146:147], s[46:47], 0, v[130:131]
	s_mov_b32 m0, s48
	s_nop 0
	global_load_lds_dwordx4 v[146:147], off
	v_lshl_add_u64 v[146:147], s[46:47], 0, v[134:135]
	s_add_i32 m0, s48, 0x2000
	s_nop 0
	global_load_lds_dwordx4 v[146:147], off
	s_waitcnt vmcnt(6)
	s_barrier
	s_setprio 1
	v_mfma_f32_16x16x32_bf16 v[52:55], v[206:209], v[166:169], v[52:55]
	v_mfma_f32_16x16x32_bf16 v[48:51], v[214:217], v[166:169], v[48:51]
	v_mfma_f32_16x16x32_bf16 v[36:39], v[206:209], v[182:185], v[36:39]
	v_mfma_f32_16x16x32_bf16 v[32:35], v[214:217], v[182:185], v[32:35]
	v_mfma_f32_16x16x32_bf16 v[20:23], v[206:209], v[190:193], v[20:23]
	v_mfma_f32_16x16x32_bf16 v[16:19], v[214:217], v[190:193], v[16:19]
	v_mfma_f32_16x16x32_bf16 v[4:7], v[206:209], v[198:201], v[4:7]
	v_mfma_f32_16x16x32_bf16 v[0:3], v[214:217], v[198:201], v[0:3]
	v_mfma_f32_16x16x32_bf16 v[52:55], v[210:213], v[170:173], v[52:55]
	v_mfma_f32_16x16x32_bf16 v[48:51], v[218:221], v[170:173], v[48:51]
	v_mfma_f32_16x16x32_bf16 v[36:39], v[210:213], v[186:189], v[36:39]
	v_mfma_f32_16x16x32_bf16 v[32:35], v[218:221], v[186:189], v[32:35]
	v_mfma_f32_16x16x32_bf16 v[20:23], v[210:213], v[194:197], v[20:23]
	v_mfma_f32_16x16x32_bf16 v[16:19], v[218:221], v[194:197], v[16:19]
	v_mfma_f32_16x16x32_bf16 v[4:7], v[210:213], v[202:205], v[4:7]
	v_mfma_f32_16x16x32_bf16 v[0:3], v[218:221], v[202:205], v[0:3]
	s_setprio 0
	s_add_i32 s46, 0, 0x18000
	v_add_u32_e32 v162, s46, v175
	s_barrier
	ds_read_b128 v[146:149], v162
	ds_read_b128 v[154:157], v162 offset:1024
	ds_read_b128 v[158:161], v162 offset:2048
	ds_read_b128 v[162:165], v162 offset:3072
	s_add_u32 s24, s24, 0x40000
	s_addc_u32 s25, s25, 0
	s_mov_b32 m0, s31
	v_lshl_add_u64 v[206:207], s[24:25], 0, v[128:129]
	ds_read_b128 v[166:169], v178 offset:32768
	ds_read_b128 v[170:173], v178 offset:33792
	ds_read_b128 v[182:185], v178 offset:34816
	ds_read_b128 v[186:189], v178 offset:35840
	ds_read_b128 v[190:193], v178 offset:36864
	ds_read_b128 v[194:197], v178 offset:37888
	ds_read_b128 v[198:201], v178 offset:38912
	ds_read_b128 v[202:205], v178 offset:39936
	global_load_lds_dwordx4 v[206:207], off
	v_lshl_add_u64 v[206:207], s[24:25], 0, v[132:133]
	s_mov_b32 m0, s33
	s_nop 0
	global_load_lds_dwordx4 v[206:207], off
	s_waitcnt lgkmcnt(8)
	s_barrier
	s_waitcnt lgkmcnt(0)
	s_setprio 1
	s_waitcnt lgkmcnt(0)
	v_mfma_f32_16x16x32_bf16 v[124:127], v[146:149], v[166:169], v[124:127]
	v_mfma_f32_16x16x32_bf16 v[120:123], v[158:161], v[166:169], v[120:123]
	v_mfma_f32_16x16x32_bf16 v[108:111], v[146:149], v[182:185], v[108:111]
	v_mfma_f32_16x16x32_bf16 v[104:107], v[158:161], v[182:185], v[104:107]
	v_mfma_f32_16x16x32_bf16 v[92:95], v[146:149], v[190:193], v[92:95]
	v_mfma_f32_16x16x32_bf16 v[88:91], v[158:161], v[190:193], v[88:91]
	v_mfma_f32_16x16x32_bf16 v[76:79], v[146:149], v[198:201], v[76:79]
	v_mfma_f32_16x16x32_bf16 v[72:75], v[158:161], v[198:201], v[72:75]
	v_mfma_f32_16x16x32_bf16 v[124:127], v[154:157], v[170:173], v[124:127]
	v_mfma_f32_16x16x32_bf16 v[120:123], v[162:165], v[170:173], v[120:123]
	v_mfma_f32_16x16x32_bf16 v[108:111], v[154:157], v[186:189], v[108:111]
	v_mfma_f32_16x16x32_bf16 v[104:107], v[162:165], v[186:189], v[104:107]
	v_mfma_f32_16x16x32_bf16 v[92:95], v[154:157], v[194:197], v[92:95]
	v_mfma_f32_16x16x32_bf16 v[88:91], v[162:165], v[194:197], v[88:91]
	v_mfma_f32_16x16x32_bf16 v[76:79], v[154:157], v[202:205], v[76:79]
	v_mfma_f32_16x16x32_bf16 v[72:75], v[162:165], v[202:205], v[72:75]
	s_setprio 0
	s_barrier
	s_add_i32 s24, 0, 0x1c000
	s_add_i32 s25, s46, s29
	v_add_u32_e32 v181, s24, v175
	v_lshl_add_u64 v[150:151], v[150:151], 0, s[4:5]
	s_mov_b32 m0, s25
	ds_read_b128 v[206:209], v181
	ds_read_b128 v[210:213], v181 offset:1024
	ds_read_b128 v[214:217], v181 offset:2048
	ds_read_b128 v[218:221], v181 offset:3072
	global_load_lds_dwordx4 v[150:151], off
	v_lshl_add_u64 v[150:151], v[222:223], 0, s[4:5]
	s_add_i32 m0, s25, 0x2000
	s_nop 0
	global_load_lds_dwordx4 v[150:151], off
	s_barrier
	s_waitcnt lgkmcnt(0)
	s_setprio 1
	s_waitcnt lgkmcnt(0)
	v_mfma_f32_16x16x32_bf16 v[116:119], v[206:209], v[166:169], v[116:119]
	v_mfma_f32_16x16x32_bf16 v[112:115], v[214:217], v[166:169], v[112:115]
	v_mfma_f32_16x16x32_bf16 v[100:103], v[206:209], v[182:185], v[100:103]
	v_mfma_f32_16x16x32_bf16 v[96:99], v[214:217], v[182:185], v[96:99]
	v_mfma_f32_16x16x32_bf16 v[84:87], v[206:209], v[190:193], v[84:87]
	v_mfma_f32_16x16x32_bf16 v[80:83], v[214:217], v[190:193], v[80:83]
	v_mfma_f32_16x16x32_bf16 v[68:71], v[206:209], v[198:201], v[68:71]
	v_mfma_f32_16x16x32_bf16 v[64:67], v[214:217], v[198:201], v[64:67]
	v_mfma_f32_16x16x32_bf16 v[116:119], v[210:213], v[170:173], v[116:119]
	v_mfma_f32_16x16x32_bf16 v[112:115], v[218:221], v[170:173], v[112:115]
	v_mfma_f32_16x16x32_bf16 v[100:103], v[210:213], v[186:189], v[100:103]
	v_mfma_f32_16x16x32_bf16 v[96:99], v[218:221], v[186:189], v[96:99]
	v_mfma_f32_16x16x32_bf16 v[84:87], v[210:213], v[194:197], v[84:87]
	v_mfma_f32_16x16x32_bf16 v[80:83], v[218:221], v[194:197], v[80:83]
	v_mfma_f32_16x16x32_bf16 v[68:71], v[210:213], v[202:205], v[68:71]
	v_mfma_f32_16x16x32_bf16 v[64:67], v[218:221], v[202:205], v[64:67]
	s_setprio 0
	s_mov_b32 m0, s35
	v_lshl_add_u64 v[150:151], v[224:225], 0, s[4:5]
	s_barrier
	ds_read_b128 v[166:169], v178 offset:49152
	ds_read_b128 v[170:173], v178 offset:50176
	ds_read_b128 v[182:185], v178 offset:51200
	ds_read_b128 v[186:189], v178 offset:52224
	ds_read_b128 v[190:193], v178 offset:53248
	ds_read_b128 v[194:197], v178 offset:54272
	ds_read_b128 v[198:201], v178 offset:55296
	ds_read_b128 v[202:205], v178 offset:56320
	global_load_lds_dwordx4 v[150:151], off
	v_lshl_add_u64 v[150:151], v[226:227], 0, s[4:5]
	s_mov_b32 m0, s36
	s_nop 0
	global_load_lds_dwordx4 v[150:151], off
	s_barrier
; #define PG8_STAGE(bufoff, gbase, voff) do { _Pragma("unroll") for (int _i = 0; _i < 2; ++_i) \
;         __builtin_amdgcn_global_load_lds((const unsigned*)((const char*)(gbase) + (voff)[_i]), (LAS unsigned*)(lds + (bufoff) + ldsw + _i * 8192), 16, 0, 0); } while (0)
; #define PG8_MMA(ai, bj, At, Bt) do { __builtin_amdgcn_s_setprio(1); _Pragma("unroll") for (int m = 0; m < 4; ++m) _Pragma("unroll") for (int n = 0; n < 2; ++n) _Pragma("unroll") for (int k = 0; k < 2; ++k) \
;         acc[ai][bj][m][n] = __builtin_amdgcn_mfma_f32_16x16x32_bf16(Bt[n][k], At[m][k], acc[ai][bj][m][n], 0, 0, 0); __builtin_amdgcn_s_setprio(0); } while (0)
; #define PG8_WAIT_V(n) asm volatile("s_waitcnt vmcnt(" #n ")" ::: "memory")
; #define PG8_WAIT_L(n) asm volatile("s_waitcnt lgkmcnt(" #n ")" ::: "memory")
; #define PG8_BAR __builtin_amdgcn_s_barrier()
; #define PG8_SCHED __builtin_amdgcn_sched_barrier(0)
;     __device__ __forceinline__ void operator()(const f32x4 (&acc)[2][2][4][2], const Unit& u, int wr, int wc, int fr, int fq, const float (&)[8]) const {
;     ...
;         const int col0 = u.pn * BM + wc * 32 + 8 * fq;
; #pragma unroll
;         for (int ai = 0; ai < 2; ++ai)
; #pragma unroll
;             for (int m = 0; m < 4; ++m) { const int row = row0 + ai * HALF + m * 16; const float rs = rsqrtf(ep[ai * 4 + m] * (1.0f / 1024.0f) + EPS);
;                 u16* rowp = O + (size_t)row * ldc + col0;
; template <class Epi>
; __device__ __forceinline__ void gemm_phase(LAS unsigned char* lds, const Gemm g, const StaticOrder& S, const Epi& E) {
;     ...
;             PG8_BAR; PG8_WAIT_L(0); PG8_MMA(1, 0, At, B0); PG8_BAR; PG8_SCHED;
;             PG8_STAGE(PG8_SB(1, 1), b3 + hstepB, voffB);
;             PG8_WAIT_V(6); PG8_BAR; PG8_MMA(1, 1, At, B1); PG8_BAR;
;         }
;         E(acc, cur, wr, wc, fr, fq, epre);
;         if (!has_next) break;
	s_waitcnt lgkmcnt(0)
	s_setprio 1
	s_waitcnt lgkmcnt(0)
	v_mfma_f32_16x16x32_bf16 v[60:63], v[146:149], v[166:169], v[60:63]
	v_mfma_f32_16x16x32_bf16 v[56:59], v[158:161], v[166:169], v[56:59]
	v_mfma_f32_16x16x32_bf16 v[44:47], v[146:149], v[182:185], v[44:47]
	v_mfma_f32_16x16x32_bf16 v[40:43], v[158:161], v[182:185], v[40:43]
	v_mfma_f32_16x16x32_bf16 v[28:31], v[146:149], v[190:193], v[28:31]
	v_mfma_f32_16x16x32_bf16 v[24:27], v[158:161], v[190:193], v[24:27]
	v_mfma_f32_16x16x32_bf16 v[12:15], v[146:149], v[198:201], v[12:15]
	v_mfma_f32_16x16x32_bf16 v[8:11], v[158:161], v[198:201], v[8:11]
	v_mfma_f32_16x16x32_bf16 v[60:63], v[154:157], v[170:173], v[60:63]
	v_mfma_f32_16x16x32_bf16 v[56:59], v[162:165], v[170:173], v[56:59]
	v_mfma_f32_16x16x32_bf16 v[44:47], v[154:157], v[186:189], v[44:47]
	v_mfma_f32_16x16x32_bf16 v[40:43], v[162:165], v[186:189], v[40:43]
	v_mfma_f32_16x16x32_bf16 v[28:31], v[154:157], v[194:197], v[28:31]
	v_mfma_f32_16x16x32_bf16 v[24:27], v[162:165], v[194:197], v[24:27]
	v_mfma_f32_16x16x32_bf16 v[12:15], v[154:157], v[202:205], v[12:15]
	v_mfma_f32_16x16x32_bf16 v[8:11], v[162:165], v[202:205], v[8:11]
	s_setprio 0
	s_barrier
	s_add_u32 s22, s22, 0x40080
	s_addc_u32 s23, s23, 0
	s_add_i32 s24, s24, s29
	v_lshl_add_u64 v[146:147], s[22:23], 0, v[130:131]
	s_mov_b32 m0, s24
	s_nop 0
	global_load_lds_dwordx4 v[146:147], off
	v_lshl_add_u64 v[146:147], s[22:23], 0, v[134:135]
	s_add_i32 m0, s24, 0x2000
	s_nop 0
	global_load_lds_dwordx4 v[146:147], off
	s_waitcnt vmcnt(6)
	s_barrier
	s_setprio 1
	v_mfma_f32_16x16x32_bf16 v[52:55], v[206:209], v[166:169], v[52:55]
	v_mfma_f32_16x16x32_bf16 v[48:51], v[214:217], v[166:169], v[48:51]
	v_mfma_f32_16x16x32_bf16 v[36:39], v[206:209], v[182:185], v[36:39]
	v_mfma_f32_16x16x32_bf16 v[32:35], v[214:217], v[182:185], v[32:35]
	v_mfma_f32_16x16x32_bf16 v[20:23], v[206:209], v[190:193], v[20:23]
	v_mfma_f32_16x16x32_bf16 v[16:19], v[214:217], v[190:193], v[16:19]
	v_mfma_f32_16x16x32_bf16 v[4:7], v[206:209], v[198:201], v[4:7]
	v_mfma_f32_16x16x32_bf16 v[0:3], v[214:217], v[198:201], v[0:3]
	v_mfma_f32_16x16x32_bf16 v[52:55], v[210:213], v[170:173], v[52:55]
	v_mfma_f32_16x16x32_bf16 v[48:51], v[218:221], v[170:173], v[48:51]
	v_mfma_f32_16x16x32_bf16 v[36:39], v[210:213], v[186:189], v[36:39]
	v_mfma_f32_16x16x32_bf16 v[32:35], v[218:221], v[186:189], v[32:35]
	v_mfma_f32_16x16x32_bf16 v[20:23], v[210:213], v[194:197], v[20:23]
	v_mfma_f32_16x16x32_bf16 v[16:19], v[218:221], v[194:197], v[16:19]
	v_mfma_f32_16x16x32_bf16 v[4:7], v[210:213], v[202:205], v[4:7]
	v_mfma_f32_16x16x32_bf16 v[0:3], v[218:221], v[202:205], v[0:3]
	s_setprio 0
	s_add_i32 s45, s45, 2
	s_add_u32 s20, s20, 0x100
	s_addc_u32 s21, s21, 0
	s_add_u32 s43, s43, 0x100
	s_addc_u32 s44, s44, 0
	s_cmp_gt_u32 s45, 13
	s_barrier
	s_cbranch_scc0 .LBB0_770
	s_bfe_u32 vcc_lo, s18, 0x20003
	s_lshl_b32 vcc_lo, vcc_lo, 10
	s_add_i32 vcc_lo, vcc_lo, 0x20010
	v_lshl_add_u32 v236, v174, 2, vcc_lo
	ds_read_b32 v228, v236
	ds_read_b32 v229, v236 offset:64
	ds_read_b32 v230, v236 offset:128
	ds_read_b32 v231, v236 offset:192
	ds_read_b32 v232, v236 offset:512
	ds_read_b32 v233, v236 offset:576
	ds_read_b32 v234, v236 offset:640
	ds_read_b32 v235, v236 offset:704
	s_waitcnt lgkmcnt(0)
	v_lshl_add_u32 v148, s18, 8, v174
	v_and_b32_e32 v236, 8, v174
	v_sub_u32_e32 v148, v148, v236
	s_mov_b32 vcc_lo, 0x10000
	s_mov_b32 vcc_hi, 0
	v_ashrrev_i32_e32 v149, 31, v148
	v_or_b32_e32 v172, 16, v148
	v_ashrrev_i32_e32 v173, 31, v172
	v_or_b32_e32 v168, 32, v148
	v_or_b32_e32 v164, 48, v148
	v_ashrrev_i32_e32 v169, 31, v168
	v_ashrrev_i32_e32 v165, 31, v164
	v_add_u32_e32 v162, 0x80, v148
	v_add_u32_e32 v156, 0x90, v148
	v_ashrrev_i32_e32 v163, 31, v162
	v_ashrrev_i32_e32 v157, 31, v156
	v_add_u32_e32 v150, 0xa0, v148
	v_ashrrev_i32_e32 v151, 31, v150
	v_add_u32_e32 v146, 0xb0, v148
	v_ashrrev_i32_e32 v147, 31, v146
	v_and_b32_e32 v237, 0x60, v176
	v_lshlrev_b32_e32 v237, 1, v237
	v_and_b32_e32 v238, 0x18, v176
	v_or_b32_e32 v237, v237, v238
	v_lshl_or_b32 v237, v236, 2, v237
	v_lshl_or_b32 v166, s40, 8, v237
	v_ashrrev_i32_e32 v167, 31, v166
	v_lshlrev_b64 v[170:171], 13, v[148:149]
	v_lshlrev_b64 v[148:149], 1, v[166:167]
	v_lshl_add_u64 v[166:167], s[96:97], 0, v[170:171]
	v_lshl_add_u64 v[212:213], v[166:167], 0, v[148:149]
	s_mov_b32 s40, s10
	s_mov_b32 s18, s12
	s_mov_b64 s[22:23], s[16:17]
	s_mov_b64 s[20:21], s[14:15]
	s_waitcnt vmcnt(8)
	s_waitcnt lgkmcnt(0)
	s_waitcnt lgkmcnt(0)
; __device__ __forceinline__ unsigned pk2(float lo, float hi) { const f32x2 v = (f32x2){lo, hi}; const bf16x2_t b = __builtin_convertvector(v, bf16x2_t); return __builtin_bit_cast(unsigned, b); }
;     __device__ __forceinline__ void operator()(const f32x4 (&acc)[2][2][4][2], const Unit& u, int wr, int wc, int fr, int fq, const float (&)[8]) const {
;     ...
;             for (int m = 0; m < 4; ++m) { const int row = row0 + ai * HALF + m * 16; const float rs = rsqrtf(ep[ai * 4 + m] * (1.0f / 1024.0f) + EPS);
;                 u16* rowp = O + (size_t)row * ldc + col0;
; #pragma unroll
;                 for (int bj = 0; bj < 2; ++bj) { f32x4 v0 = acc[ai][bj][m][0] * rs, v1 = acc[ai][bj][m][1] * rs;
;                     if (ACT == 1) {
; #pragma unroll
;                         for (int j = 0; j < 4; ++j) { const float a0 = fmaxf(v0[j], 0.f), a1 = fmaxf(v1[j], 0.f); v0[j] = a0 * a0; v1[j] = a1 * a1; } }
;                     u32x4 w; w.x = pk2(v0[0], v0[1]); w.y = pk2(v0[2], v0[3]); w.z = pk2(v1[0], v1[1]); w.w = pk2(v1[2], v1[3]);
;                     *(u32x4*)(rowp + bj * HALF) = w; } }
	v_mov_b32_e32 v184, v228
	v_pk_mul_f32 v[120:121], v[120:121], v[184:185] op_sel_hi:[1,0]
	v_pk_mul_f32 v[126:127], v[126:127], v[184:185] op_sel_hi:[1,0]
	v_pk_mul_f32 v[124:125], v[124:125], v[184:185] op_sel_hi:[1,0]
	v_pk_mul_f32 v[122:123], v[122:123], v[184:185] op_sel_hi:[1,0]
	v_max_f32_e32 v120, 0, v120
	v_max_f32_e32 v121, 0, v121
	v_max_f32_e32 v124, 0, v124
	v_max_f32_e32 v125, 0, v125
	v_pk_mul_f32 v[190:191], v[120:121], v[120:121]
	v_max_f32_e32 v120, 0, v126
	v_max_f32_e32 v122, 0, v122
	v_max_f32_e32 v121, 0, v127
	v_max_f32_e32 v123, 0, v123
	v_pk_mul_f32 v[124:125], v[124:125], v[124:125]
	v_pk_mul_f32 v[126:127], v[120:121], v[120:121]
	v_pk_mul_f32 v[194:195], v[122:123], v[122:123]
	v_pk_mul_f32 v[114:115], v[114:115], v[184:185] op_sel_hi:[1,0]
	v_cvt_pk_bf16_f32 v238, v124, v125
	v_cvt_pk_bf16_f32 v239, v126, v127
	v_cvt_pk_bf16_f32 v240, v190, v191
	v_cvt_pk_bf16_f32 v241, v194, v195
	v_pk_mul_f32 v[116:117], v[116:117], v[184:185] op_sel_hi:[1,0]
	v_pk_mul_f32 v[112:113], v[112:113], v[184:185] op_sel_hi:[1,0]
	v_max_f32_e32 v114, 0, v114
	v_max_f32_e32 v115, 0, v115
	v_pk_mul_f32 v[118:119], v[118:119], v[184:185] op_sel_hi:[1,0]
	v_max_f32_e32 v116, 0, v116
	v_max_f32_e32 v112, 0, v112
	v_max_f32_e32 v117, 0, v117
	v_max_f32_e32 v113, 0, v113
	v_pk_mul_f32 v[122:123], v[114:115], v[114:115]
	v_pk_mul_f32 v[116:117], v[116:117], v[116:117]
	v_pk_mul_f32 v[120:121], v[112:113], v[112:113]
	v_max_f32_e32 v112, 0, v118
	v_max_f32_e32 v113, 0, v119
	v_pk_mul_f32 v[118:119], v[112:113], v[112:113]
	v_cvt_pk_bf16_f32 v242, v116, v117
	v_cvt_pk_bf16_f32 v243, v118, v119
	v_cvt_pk_bf16_f32 v244, v120, v121
	v_cvt_pk_bf16_f32 v245, v122, v123
	v_mov_b32_e32 v246, v238
	v_mov_b32_e32 v247, v239
	v_mov_b32_e32 v248, v240
	v_mov_b32_e32 v249, v241
	v_mov_b32_dpp v238, v242 row_shr:8 row_mask:0xf bank_mask:0xc
	v_mov_b32_dpp v239, v243 row_shr:8 row_mask:0xf bank_mask:0xc
	v_mov_b32_dpp v240, v244 row_shr:8 row_mask:0xf bank_mask:0xc
	v_mov_b32_dpp v241, v245 row_shr:8 row_mask:0xf bank_mask:0xc
	global_store_dwordx4 v[212:213], v[238:241], off
	v_lshl_add_u64 v[236:237], v[212:213], 0, vcc
	v_mov_b32_dpp v242, v246 row_shl:8 row_mask:0xf bank_mask:0x3
	v_mov_b32_dpp v243, v247 row_shl:8 row_mask:0xf bank_mask:0x3
	v_mov_b32_dpp v244, v248 row_shl:8 row_mask:0xf bank_mask:0x3
	v_mov_b32_dpp v245, v249 row_shl:8 row_mask:0xf bank_mask:0x3
	global_store_dwordx4 v[236:237], v[242:245], off
	s_nop 1
	v_mov_b32_e32 v112, v229
	v_pk_mul_f32 v[104:105], v[104:105], v[112:113] op_sel_hi:[1,0]
	v_pk_mul_f32 v[110:111], v[110:111], v[112:113] op_sel_hi:[1,0]
	v_pk_mul_f32 v[108:109], v[108:109], v[112:113] op_sel_hi:[1,0]
	v_pk_mul_f32 v[106:107], v[106:107], v[112:113] op_sel_hi:[1,0]
	v_max_f32_e32 v104, 0, v104
	v_max_f32_e32 v105, 0, v105
	v_lshlrev_b64 v[114:115], 13, v[172:173]
	v_max_f32_e32 v108, 0, v108
	v_max_f32_e32 v109, 0, v109
	v_pk_mul_f32 v[116:117], v[104:105], v[104:105]
	v_max_f32_e32 v104, 0, v110
	v_max_f32_e32 v106, 0, v106
	v_max_f32_e32 v105, 0, v111
	v_max_f32_e32 v107, 0, v107
	v_lshl_add_u64 v[114:115], s[96:97], 0, v[114:115]
	v_pk_mul_f32 v[108:109], v[108:109], v[108:109]
	v_pk_mul_f32 v[110:111], v[104:105], v[104:105]
	v_pk_mul_f32 v[118:119], v[106:107], v[106:107]
	v_pk_mul_f32 v[96:97], v[96:97], v[112:113] op_sel_hi:[1,0]
	v_lshl_add_u64 v[114:115], v[114:115], 0, v[148:149]
	v_cvt_pk_bf16_f32 v238, v108, v109
	v_cvt_pk_bf16_f32 v239, v110, v111
	v_cvt_pk_bf16_f32 v240, v116, v117
	v_cvt_pk_bf16_f32 v241, v118, v119
	v_pk_mul_f32 v[102:103], v[102:103], v[112:113] op_sel_hi:[1,0]
	v_max_f32_e32 v96, 0, v96
	v_max_f32_e32 v97, 0, v97
	v_pk_mul_f32 v[100:101], v[100:101], v[112:113] op_sel_hi:[1,0]
	v_pk_mul_f32 v[98:99], v[98:99], v[112:113] op_sel_hi:[1,0]
	v_pk_mul_f32 v[104:105], v[96:97], v[96:97]
	v_max_f32_e32 v96, 0, v102
	v_max_f32_e32 v97, 0, v103
	v_max_f32_e32 v100, 0, v100
	v_max_f32_e32 v101, 0, v101
	v_pk_mul_f32 v[100:101], v[100:101], v[100:101]
	v_pk_mul_f32 v[108:109], v[96:97], v[96:97]
	v_cvt_pk_bf16_f32 v242, v100, v101
	s_waitcnt lgkmcnt(0)
	v_max_f32_e32 v98, 0, v98
	v_max_f32_e32 v99, 0, v99
	v_pk_mul_f32 v[110:111], v[98:99], v[98:99]
	v_cvt_pk_bf16_f32 v243, v108, v109
	v_cvt_pk_bf16_f32 v244, v104, v105
	v_cvt_pk_bf16_f32 v245, v110, v111
	v_mov_b32_e32 v246, v238
	v_mov_b32_e32 v247, v239
	v_mov_b32_e32 v248, v240
	v_mov_b32_e32 v249, v241
	v_mov_b32_dpp v238, v242 row_shr:8 row_mask:0xf bank_mask:0xc
	v_mov_b32_dpp v239, v243 row_shr:8 row_mask:0xf bank_mask:0xc
	v_mov_b32_dpp v240, v244 row_shr:8 row_mask:0xf bank_mask:0xc
	v_mov_b32_dpp v241, v245 row_shr:8 row_mask:0xf bank_mask:0xc
	global_store_dwordx4 v[114:115], v[238:241], off
	v_lshl_add_u64 v[236:237], v[114:115], 0, vcc
	v_mov_b32_dpp v242, v246 row_shl:8 row_mask:0xf bank_mask:0x3
	v_mov_b32_dpp v243, v247 row_shl:8 row_mask:0xf bank_mask:0x3
	v_mov_b32_dpp v244, v248 row_shl:8 row_mask:0xf bank_mask:0x3
	v_mov_b32_dpp v245, v249 row_shl:8 row_mask:0xf bank_mask:0x3
	global_store_dwordx4 v[236:237], v[242:245], off
	s_waitcnt lgkmcnt(0)
; __device__ __forceinline__ unsigned pk2(float lo, float hi) { const f32x2 v = (f32x2){lo, hi}; const bf16x2_t b = __builtin_convertvector(v, bf16x2_t); return __builtin_bit_cast(unsigned, b); }
;     __device__ __forceinline__ void operator()(const f32x4 (&acc)[2][2][4][2], const Unit& u, int wr, int wc, int fr, int fq, const float (&)[8]) const {
;     ...
;             for (int m = 0; m < 4; ++m) { const int row = row0 + ai * HALF + m * 16; const float rs = rsqrtf(ep[ai * 4 + m] * (1.0f / 1024.0f) + EPS);
;                 u16* rowp = O + (size_t)row * ldc + col0;
; #pragma unroll
;                 for (int bj = 0; bj < 2; ++bj) { f32x4 v0 = acc[ai][bj][m][0] * rs, v1 = acc[ai][bj][m][1] * rs;
;                     if (ACT == 1) {
; #pragma unroll
;                         for (int j = 0; j < 4; ++j) { const float a0 = fmaxf(v0[j], 0.f), a1 = fmaxf(v1[j], 0.f); v0[j] = a0 * a0; v1[j] = a1 * a1; } }
;                     u32x4 w; w.x = pk2(v0[0], v0[1]); w.y = pk2(v0[2], v0[3]); w.z = pk2(v1[0], v1[1]); w.w = pk2(v1[2], v1[3]);
;                     *(u32x4*)(rowp + bj * HALF) = w; } }
	s_nop 0
	s_nop 0
	s_nop 0
	s_nop 1
	v_lshlrev_b64 v[98:99], 13, v[168:169]
	v_lshl_add_u64 v[98:99], s[96:97], 0, v[98:99]
	v_lshl_add_u64 v[98:99], v[98:99], 0, v[148:149]
	v_mov_b32_e32 v100, v230
	v_pk_mul_f32 v[88:89], v[88:89], v[100:101] op_sel_hi:[1,0]
	v_pk_mul_f32 v[94:95], v[94:95], v[100:101] op_sel_hi:[1,0]
	v_pk_mul_f32 v[92:93], v[92:93], v[100:101] op_sel_hi:[1,0]
	v_pk_mul_f32 v[90:91], v[90:91], v[100:101] op_sel_hi:[1,0]
	v_max_f32_e32 v88, 0, v88
	v_max_f32_e32 v89, 0, v89
	v_max_f32_e32 v92, 0, v92
	v_max_f32_e32 v93, 0, v93
	v_pk_mul_f32 v[102:103], v[88:89], v[88:89]
	v_max_f32_e32 v88, 0, v94
	v_max_f32_e32 v90, 0, v90
	v_max_f32_e32 v89, 0, v95
	v_max_f32_e32 v91, 0, v91
	v_pk_mul_f32 v[92:93], v[92:93], v[92:93]
	v_pk_mul_f32 v[94:95], v[88:89], v[88:89]
	v_pk_mul_f32 v[104:105], v[90:91], v[90:91]
	v_pk_mul_f32 v[82:83], v[82:83], v[100:101] op_sel_hi:[1,0]
	v_cvt_pk_bf16_f32 v238, v92, v93
	v_cvt_pk_bf16_f32 v239, v94, v95
	v_cvt_pk_bf16_f32 v240, v102, v103
	v_cvt_pk_bf16_f32 v241, v104, v105
	v_pk_mul_f32 v[84:85], v[84:85], v[100:101] op_sel_hi:[1,0]
	v_pk_mul_f32 v[80:81], v[80:81], v[100:101] op_sel_hi:[1,0]
	v_max_f32_e32 v82, 0, v82
	v_max_f32_e32 v83, 0, v83
	v_pk_mul_f32 v[86:87], v[86:87], v[100:101] op_sel_hi:[1,0]
	v_max_f32_e32 v84, 0, v84
	v_max_f32_e32 v80, 0, v80
	v_max_f32_e32 v85, 0, v85
	v_max_f32_e32 v81, 0, v81
	v_pk_mul_f32 v[90:91], v[82:83], v[82:83]
	v_pk_mul_f32 v[84:85], v[84:85], v[84:85]
	v_pk_mul_f32 v[88:89], v[80:81], v[80:81]
	v_max_f32_e32 v80, 0, v86
	v_max_f32_e32 v81, 0, v87
	v_pk_mul_f32 v[86:87], v[80:81], v[80:81]
	v_cvt_pk_bf16_f32 v242, v84, v85
	v_cvt_pk_bf16_f32 v243, v86, v87
	v_cvt_pk_bf16_f32 v244, v88, v89
	v_cvt_pk_bf16_f32 v245, v90, v91
	v_mov_b32_e32 v246, v238
	v_mov_b32_e32 v247, v239
	v_mov_b32_e32 v248, v240
	v_mov_b32_e32 v249, v241
	v_mov_b32_dpp v238, v242 row_shr:8 row_mask:0xf bank_mask:0xc
	v_mov_b32_dpp v239, v243 row_shr:8 row_mask:0xf bank_mask:0xc
	v_mov_b32_dpp v240, v244 row_shr:8 row_mask:0xf bank_mask:0xc
	v_mov_b32_dpp v241, v245 row_shr:8 row_mask:0xf bank_mask:0xc
	global_store_dwordx4 v[98:99], v[238:241], off
	v_lshl_add_u64 v[236:237], v[98:99], 0, vcc
	v_mov_b32_dpp v242, v246 row_shl:8 row_mask:0xf bank_mask:0x3
	v_mov_b32_dpp v243, v247 row_shl:8 row_mask:0xf bank_mask:0x3
	v_mov_b32_dpp v244, v248 row_shl:8 row_mask:0xf bank_mask:0x3
	v_mov_b32_dpp v245, v249 row_shl:8 row_mask:0xf bank_mask:0x3
	global_store_dwordx4 v[236:237], v[242:245], off
	s_nop 1
	v_mov_b32_e32 v80, v231
	v_pk_mul_f32 v[72:73], v[72:73], v[80:81] op_sel_hi:[1,0]
	v_pk_mul_f32 v[78:79], v[78:79], v[80:81] op_sel_hi:[1,0]
	v_pk_mul_f32 v[76:77], v[76:77], v[80:81] op_sel_hi:[1,0]
	v_pk_mul_f32 v[74:75], v[74:75], v[80:81] op_sel_hi:[1,0]
	v_max_f32_e32 v72, 0, v72
	v_max_f32_e32 v73, 0, v73
	v_lshlrev_b64 v[82:83], 13, v[164:165]
	v_max_f32_e32 v76, 0, v76
	v_max_f32_e32 v77, 0, v77
	v_pk_mul_f32 v[84:85], v[72:73], v[72:73]
	v_max_f32_e32 v72, 0, v78
	v_max_f32_e32 v74, 0, v74
	v_max_f32_e32 v73, 0, v79
	v_max_f32_e32 v75, 0, v75
	v_lshl_add_u64 v[82:83], s[96:97], 0, v[82:83]
	v_pk_mul_f32 v[76:77], v[76:77], v[76:77]
	v_pk_mul_f32 v[78:79], v[72:73], v[72:73]
	v_pk_mul_f32 v[86:87], v[74:75], v[74:75]
	v_pk_mul_f32 v[64:65], v[64:65], v[80:81] op_sel_hi:[1,0]
	v_lshl_add_u64 v[82:83], v[82:83], 0, v[148:149]
	v_cvt_pk_bf16_f32 v238, v76, v77
	v_cvt_pk_bf16_f32 v239, v78, v79
	v_cvt_pk_bf16_f32 v240, v84, v85
	v_cvt_pk_bf16_f32 v241, v86, v87
	v_pk_mul_f32 v[70:71], v[70:71], v[80:81] op_sel_hi:[1,0]
	v_max_f32_e32 v64, 0, v64
	v_max_f32_e32 v65, 0, v65
	v_pk_mul_f32 v[68:69], v[68:69], v[80:81] op_sel_hi:[1,0]
	v_pk_mul_f32 v[66:67], v[66:67], v[80:81] op_sel_hi:[1,0]
	v_pk_mul_f32 v[72:73], v[64:65], v[64:65]
	v_max_f32_e32 v64, 0, v70
	v_max_f32_e32 v65, 0, v71
	v_max_f32_e32 v68, 0, v68
	v_max_f32_e32 v69, 0, v69
	v_pk_mul_f32 v[68:69], v[68:69], v[68:69]
	v_pk_mul_f32 v[76:77], v[64:65], v[64:65]
	v_cvt_pk_bf16_f32 v242, v68, v69
	s_waitcnt lgkmcnt(0)
	v_max_f32_e32 v66, 0, v66
	v_max_f32_e32 v67, 0, v67
	v_pk_mul_f32 v[78:79], v[66:67], v[66:67]
	v_cvt_pk_bf16_f32 v243, v76, v77
	v_cvt_pk_bf16_f32 v244, v72, v73
	v_cvt_pk_bf16_f32 v245, v78, v79
	v_mov_b32_e32 v246, v238
	v_mov_b32_e32 v247, v239
	v_mov_b32_e32 v248, v240
	v_mov_b32_e32 v249, v241
	v_mov_b32_dpp v238, v242 row_shr:8 row_mask:0xf bank_mask:0xc
	v_mov_b32_dpp v239, v243 row_shr:8 row_mask:0xf bank_mask:0xc
	v_mov_b32_dpp v240, v244 row_shr:8 row_mask:0xf bank_mask:0xc
	v_mov_b32_dpp v241, v245 row_shr:8 row_mask:0xf bank_mask:0xc
	global_store_dwordx4 v[82:83], v[238:241], off
	v_lshl_add_u64 v[236:237], v[82:83], 0, vcc
	v_mov_b32_dpp v242, v246 row_shl:8 row_mask:0xf bank_mask:0x3
	v_mov_b32_dpp v243, v247 row_shl:8 row_mask:0xf bank_mask:0x3
	v_mov_b32_dpp v244, v248 row_shl:8 row_mask:0xf bank_mask:0x3
	v_mov_b32_dpp v245, v249 row_shl:8 row_mask:0xf bank_mask:0x3
	global_store_dwordx4 v[236:237], v[242:245], off
	s_waitcnt lgkmcnt(0)
; __device__ __forceinline__ unsigned pk2(float lo, float hi) { const f32x2 v = (f32x2){lo, hi}; const bf16x2_t b = __builtin_convertvector(v, bf16x2_t); return __builtin_bit_cast(unsigned, b); }
;     __device__ __forceinline__ void operator()(const f32x4 (&acc)[2][2][4][2], const Unit& u, int wr, int wc, int fr, int fq, const float (&)[8]) const {
;     ...
;             for (int m = 0; m < 4; ++m) { const int row = row0 + ai * HALF + m * 16; const float rs = rsqrtf(ep[ai * 4 + m] * (1.0f / 1024.0f) + EPS);
;                 u16* rowp = O + (size_t)row * ldc + col0;
; #pragma unroll
;                 for (int bj = 0; bj < 2; ++bj) { f32x4 v0 = acc[ai][bj][m][0] * rs, v1 = acc[ai][bj][m][1] * rs;
;                     if (ACT == 1) {
; #pragma unroll
;                         for (int j = 0; j < 4; ++j) { const float a0 = fmaxf(v0[j], 0.f), a1 = fmaxf(v1[j], 0.f); v0[j] = a0 * a0; v1[j] = a1 * a1; } }
;                     u32x4 w; w.x = pk2(v0[0], v0[1]); w.y = pk2(v0[2], v0[3]); w.z = pk2(v1[0], v1[1]); w.w = pk2(v1[2], v1[3]);
;                     *(u32x4*)(rowp + bj * HALF) = w; } }
	s_nop 0
	s_nop 0
	s_nop 0
	s_nop 1
	v_lshlrev_b64 v[66:67], 13, v[162:163]
	v_lshl_add_u64 v[66:67], s[96:97], 0, v[66:67]
	v_lshl_add_u64 v[66:67], v[66:67], 0, v[148:149]
	v_mov_b32_e32 v68, v232
	v_pk_mul_f32 v[56:57], v[56:57], v[68:69] op_sel_hi:[1,0]
	v_pk_mul_f32 v[62:63], v[62:63], v[68:69] op_sel_hi:[1,0]
	v_pk_mul_f32 v[60:61], v[60:61], v[68:69] op_sel_hi:[1,0]
	v_pk_mul_f32 v[58:59], v[58:59], v[68:69] op_sel_hi:[1,0]
	v_max_f32_e32 v56, 0, v56
	v_max_f32_e32 v57, 0, v57
	v_max_f32_e32 v60, 0, v60
	v_max_f32_e32 v61, 0, v61
	v_pk_mul_f32 v[70:71], v[56:57], v[56:57]
	v_max_f32_e32 v56, 0, v62
	v_max_f32_e32 v58, 0, v58
	v_max_f32_e32 v57, 0, v63
	v_max_f32_e32 v59, 0, v59
	v_pk_mul_f32 v[60:61], v[60:61], v[60:61]
	v_pk_mul_f32 v[62:63], v[56:57], v[56:57]
	v_pk_mul_f32 v[72:73], v[58:59], v[58:59]
	v_pk_mul_f32 v[50:51], v[50:51], v[68:69] op_sel_hi:[1,0]
	v_cvt_pk_bf16_f32 v238, v60, v61
	v_cvt_pk_bf16_f32 v239, v62, v63
	v_cvt_pk_bf16_f32 v240, v70, v71
	v_cvt_pk_bf16_f32 v241, v72, v73
	v_pk_mul_f32 v[52:53], v[52:53], v[68:69] op_sel_hi:[1,0]
	v_pk_mul_f32 v[48:49], v[48:49], v[68:69] op_sel_hi:[1,0]
	v_max_f32_e32 v50, 0, v50
	v_max_f32_e32 v51, 0, v51
	v_pk_mul_f32 v[54:55], v[54:55], v[68:69] op_sel_hi:[1,0]
	v_max_f32_e32 v52, 0, v52
	v_max_f32_e32 v48, 0, v48
	v_max_f32_e32 v53, 0, v53
	v_max_f32_e32 v49, 0, v49
	v_pk_mul_f32 v[58:59], v[50:51], v[50:51]
	v_pk_mul_f32 v[52:53], v[52:53], v[52:53]
	v_pk_mul_f32 v[56:57], v[48:49], v[48:49]
	v_max_f32_e32 v48, 0, v54
	v_max_f32_e32 v49, 0, v55
	v_pk_mul_f32 v[54:55], v[48:49], v[48:49]
	v_cvt_pk_bf16_f32 v242, v52, v53
	v_cvt_pk_bf16_f32 v243, v54, v55
	v_cvt_pk_bf16_f32 v244, v56, v57
	v_cvt_pk_bf16_f32 v245, v58, v59
	v_mov_b32_e32 v246, v238
	v_mov_b32_e32 v247, v239
	v_mov_b32_e32 v248, v240
	v_mov_b32_e32 v249, v241
	v_mov_b32_dpp v238, v242 row_shr:8 row_mask:0xf bank_mask:0xc
	v_mov_b32_dpp v239, v243 row_shr:8 row_mask:0xf bank_mask:0xc
	v_mov_b32_dpp v240, v244 row_shr:8 row_mask:0xf bank_mask:0xc
	v_mov_b32_dpp v241, v245 row_shr:8 row_mask:0xf bank_mask:0xc
	global_store_dwordx4 v[66:67], v[238:241], off
	v_lshl_add_u64 v[236:237], v[66:67], 0, vcc
	v_mov_b32_dpp v242, v246 row_shl:8 row_mask:0xf bank_mask:0x3
	v_mov_b32_dpp v243, v247 row_shl:8 row_mask:0xf bank_mask:0x3
	v_mov_b32_dpp v244, v248 row_shl:8 row_mask:0xf bank_mask:0x3
	v_mov_b32_dpp v245, v249 row_shl:8 row_mask:0xf bank_mask:0x3
	global_store_dwordx4 v[236:237], v[242:245], off
	s_nop 1
	v_mov_b32_e32 v48, v233
	v_pk_mul_f32 v[40:41], v[40:41], v[48:49] op_sel_hi:[1,0]
	v_pk_mul_f32 v[46:47], v[46:47], v[48:49] op_sel_hi:[1,0]
	v_pk_mul_f32 v[44:45], v[44:45], v[48:49] op_sel_hi:[1,0]
	v_pk_mul_f32 v[42:43], v[42:43], v[48:49] op_sel_hi:[1,0]
	v_max_f32_e32 v40, 0, v40
	v_max_f32_e32 v41, 0, v41
	v_lshlrev_b64 v[50:51], 13, v[156:157]
	v_max_f32_e32 v44, 0, v44
	v_max_f32_e32 v45, 0, v45
	v_pk_mul_f32 v[52:53], v[40:41], v[40:41]
	v_max_f32_e32 v40, 0, v46
	v_max_f32_e32 v42, 0, v42
	v_max_f32_e32 v41, 0, v47
	v_max_f32_e32 v43, 0, v43
	v_lshl_add_u64 v[50:51], s[96:97], 0, v[50:51]
	v_pk_mul_f32 v[44:45], v[44:45], v[44:45]
	v_pk_mul_f32 v[46:47], v[40:41], v[40:41]
	v_pk_mul_f32 v[54:55], v[42:43], v[42:43]
	v_pk_mul_f32 v[32:33], v[32:33], v[48:49] op_sel_hi:[1,0]
	v_lshl_add_u64 v[50:51], v[50:51], 0, v[148:149]
	v_cvt_pk_bf16_f32 v238, v44, v45
	v_cvt_pk_bf16_f32 v239, v46, v47
	v_cvt_pk_bf16_f32 v240, v52, v53
	v_cvt_pk_bf16_f32 v241, v54, v55
	v_pk_mul_f32 v[38:39], v[38:39], v[48:49] op_sel_hi:[1,0]
	v_max_f32_e32 v32, 0, v32
	v_max_f32_e32 v33, 0, v33
	v_pk_mul_f32 v[36:37], v[36:37], v[48:49] op_sel_hi:[1,0]
	v_pk_mul_f32 v[34:35], v[34:35], v[48:49] op_sel_hi:[1,0]
	v_pk_mul_f32 v[40:41], v[32:33], v[32:33]
	v_max_f32_e32 v32, 0, v38
	v_max_f32_e32 v33, 0, v39
	v_max_f32_e32 v36, 0, v36
	v_max_f32_e32 v37, 0, v37
	v_pk_mul_f32 v[36:37], v[36:37], v[36:37]
	v_pk_mul_f32 v[44:45], v[32:33], v[32:33]
	v_cvt_pk_bf16_f32 v242, v36, v37
	s_waitcnt lgkmcnt(0)
	v_max_f32_e32 v34, 0, v34
	v_max_f32_e32 v35, 0, v35
	v_pk_mul_f32 v[46:47], v[34:35], v[34:35]
	v_cvt_pk_bf16_f32 v243, v44, v45
	v_cvt_pk_bf16_f32 v244, v40, v41
	v_cvt_pk_bf16_f32 v245, v46, v47
	v_mov_b32_e32 v246, v238
	v_mov_b32_e32 v247, v239
	v_mov_b32_e32 v248, v240
	v_mov_b32_e32 v249, v241
	v_mov_b32_dpp v238, v242 row_shr:8 row_mask:0xf bank_mask:0xc
	v_mov_b32_dpp v239, v243 row_shr:8 row_mask:0xf bank_mask:0xc
	v_mov_b32_dpp v240, v244 row_shr:8 row_mask:0xf bank_mask:0xc
	v_mov_b32_dpp v241, v245 row_shr:8 row_mask:0xf bank_mask:0xc
	global_store_dwordx4 v[50:51], v[238:241], off
	v_lshl_add_u64 v[236:237], v[50:51], 0, vcc
	v_mov_b32_dpp v242, v246 row_shl:8 row_mask:0xf bank_mask:0x3
	v_mov_b32_dpp v243, v247 row_shl:8 row_mask:0xf bank_mask:0x3
	v_mov_b32_dpp v244, v248 row_shl:8 row_mask:0xf bank_mask:0x3
	v_mov_b32_dpp v245, v249 row_shl:8 row_mask:0xf bank_mask:0x3
	global_store_dwordx4 v[236:237], v[242:245], off
	s_waitcnt lgkmcnt(0)
; __device__ __forceinline__ unsigned pk2(float lo, float hi) { const f32x2 v = (f32x2){lo, hi}; const bf16x2_t b = __builtin_convertvector(v, bf16x2_t); return __builtin_bit_cast(unsigned, b); }
;     __device__ __forceinline__ void operator()(const f32x4 (&acc)[2][2][4][2], const Unit& u, int wr, int wc, int fr, int fq, const float (&)[8]) const {
;     ...
;             for (int m = 0; m < 4; ++m) { const int row = row0 + ai * HALF + m * 16; const float rs = rsqrtf(ep[ai * 4 + m] * (1.0f / 1024.0f) + EPS);
;                 u16* rowp = O + (size_t)row * ldc + col0;
; #pragma unroll
;                 for (int bj = 0; bj < 2; ++bj) { f32x4 v0 = acc[ai][bj][m][0] * rs, v1 = acc[ai][bj][m][1] * rs;
;                     if (ACT == 1) {
; #pragma unroll
;                         for (int j = 0; j < 4; ++j) { const float a0 = fmaxf(v0[j], 0.f), a1 = fmaxf(v1[j], 0.f); v0[j] = a0 * a0; v1[j] = a1 * a1; } }
;                     u32x4 w; w.x = pk2(v0[0], v0[1]); w.y = pk2(v0[2], v0[3]); w.z = pk2(v1[0], v1[1]); w.w = pk2(v1[2], v1[3]);
;                     *(u32x4*)(rowp + bj * HALF) = w; } }
; template <class Epi>
; __device__ __forceinline__ void gemm_phase(LAS unsigned char* lds, const Gemm g, const StaticOrder& S, const Epi& E) {
;     ...
;         E(acc, cur, wr, wc, fr, fq, epre);
;         if (!has_next) break;
	s_nop 0
	s_nop 0
	s_nop 0
	s_nop 1
	v_lshlrev_b64 v[34:35], 13, v[150:151]
	v_lshl_add_u64 v[34:35], s[96:97], 0, v[34:35]
	v_lshl_add_u64 v[34:35], v[34:35], 0, v[148:149]
	v_mov_b32_e32 v36, v234
	v_pk_mul_f32 v[24:25], v[24:25], v[36:37] op_sel_hi:[1,0]
	v_pk_mul_f32 v[30:31], v[30:31], v[36:37] op_sel_hi:[1,0]
	v_pk_mul_f32 v[28:29], v[28:29], v[36:37] op_sel_hi:[1,0]
	v_pk_mul_f32 v[26:27], v[26:27], v[36:37] op_sel_hi:[1,0]
	v_max_f32_e32 v24, 0, v24
	v_max_f32_e32 v25, 0, v25
	v_max_f32_e32 v28, 0, v28
	v_max_f32_e32 v29, 0, v29
	v_pk_mul_f32 v[38:39], v[24:25], v[24:25]
	v_max_f32_e32 v24, 0, v30
	v_max_f32_e32 v26, 0, v26
	v_max_f32_e32 v25, 0, v31
	v_max_f32_e32 v27, 0, v27
	v_pk_mul_f32 v[28:29], v[28:29], v[28:29]
	v_pk_mul_f32 v[30:31], v[24:25], v[24:25]
	v_pk_mul_f32 v[40:41], v[26:27], v[26:27]
	v_pk_mul_f32 v[18:19], v[18:19], v[36:37] op_sel_hi:[1,0]
	v_cvt_pk_bf16_f32 v238, v28, v29
	v_cvt_pk_bf16_f32 v239, v30, v31
	v_cvt_pk_bf16_f32 v240, v38, v39
	v_cvt_pk_bf16_f32 v241, v40, v41
	v_pk_mul_f32 v[20:21], v[20:21], v[36:37] op_sel_hi:[1,0]
	v_pk_mul_f32 v[16:17], v[16:17], v[36:37] op_sel_hi:[1,0]
	v_max_f32_e32 v18, 0, v18
	v_max_f32_e32 v19, 0, v19
	v_pk_mul_f32 v[22:23], v[22:23], v[36:37] op_sel_hi:[1,0]
	v_max_f32_e32 v20, 0, v20
	v_max_f32_e32 v16, 0, v16
	v_max_f32_e32 v21, 0, v21
	v_max_f32_e32 v17, 0, v17
	v_pk_mul_f32 v[26:27], v[18:19], v[18:19]
	v_pk_mul_f32 v[20:21], v[20:21], v[20:21]
	v_pk_mul_f32 v[24:25], v[16:17], v[16:17]
	v_max_f32_e32 v16, 0, v22
	v_max_f32_e32 v17, 0, v23
	v_pk_mul_f32 v[22:23], v[16:17], v[16:17]
	v_cvt_pk_bf16_f32 v242, v20, v21
	v_cvt_pk_bf16_f32 v243, v22, v23
	v_cvt_pk_bf16_f32 v244, v24, v25
	v_cvt_pk_bf16_f32 v245, v26, v27
	v_mov_b32_e32 v246, v238
	v_mov_b32_e32 v247, v239
	v_mov_b32_e32 v248, v240
	v_mov_b32_e32 v249, v241
	v_mov_b32_dpp v238, v242 row_shr:8 row_mask:0xf bank_mask:0xc
	v_mov_b32_dpp v239, v243 row_shr:8 row_mask:0xf bank_mask:0xc
	v_mov_b32_dpp v240, v244 row_shr:8 row_mask:0xf bank_mask:0xc
	v_mov_b32_dpp v241, v245 row_shr:8 row_mask:0xf bank_mask:0xc
	global_store_dwordx4 v[34:35], v[238:241], off
	v_lshl_add_u64 v[236:237], v[34:35], 0, vcc
	v_mov_b32_dpp v242, v246 row_shl:8 row_mask:0xf bank_mask:0x3
	v_mov_b32_dpp v243, v247 row_shl:8 row_mask:0xf bank_mask:0x3
	v_mov_b32_dpp v244, v248 row_shl:8 row_mask:0xf bank_mask:0x3
	v_mov_b32_dpp v245, v249 row_shl:8 row_mask:0xf bank_mask:0x3
	global_store_dwordx4 v[236:237], v[242:245], off
	s_nop 1
	v_mov_b32_e32 v16, v235
	v_pk_mul_f32 v[8:9], v[8:9], v[16:17] op_sel_hi:[1,0]
	v_pk_mul_f32 v[14:15], v[14:15], v[16:17] op_sel_hi:[1,0]
	v_pk_mul_f32 v[12:13], v[12:13], v[16:17] op_sel_hi:[1,0]
	v_pk_mul_f32 v[10:11], v[10:11], v[16:17] op_sel_hi:[1,0]
	v_max_f32_e32 v8, 0, v8
	v_max_f32_e32 v9, 0, v9
	v_lshlrev_b64 v[18:19], 13, v[146:147]
	v_max_f32_e32 v12, 0, v12
	v_max_f32_e32 v13, 0, v13
	v_pk_mul_f32 v[20:21], v[8:9], v[8:9]
	v_max_f32_e32 v8, 0, v14
	v_max_f32_e32 v10, 0, v10
	v_max_f32_e32 v9, 0, v15
	v_max_f32_e32 v11, 0, v11
	v_lshl_add_u64 v[18:19], s[96:97], 0, v[18:19]
	v_pk_mul_f32 v[12:13], v[12:13], v[12:13]
	v_pk_mul_f32 v[14:15], v[8:9], v[8:9]
	v_pk_mul_f32 v[22:23], v[10:11], v[10:11]
	v_pk_mul_f32 v[0:1], v[0:1], v[16:17] op_sel_hi:[1,0]
	v_lshl_add_u64 v[18:19], v[18:19], 0, v[148:149]
	v_cvt_pk_bf16_f32 v238, v12, v13
	v_cvt_pk_bf16_f32 v239, v14, v15
	v_cvt_pk_bf16_f32 v240, v20, v21
	v_cvt_pk_bf16_f32 v241, v22, v23
	v_pk_mul_f32 v[6:7], v[6:7], v[16:17] op_sel_hi:[1,0]
	v_pk_mul_f32 v[4:5], v[4:5], v[16:17] op_sel_hi:[1,0]
	v_pk_mul_f32 v[2:3], v[2:3], v[16:17] op_sel_hi:[1,0]
	v_max_f32_e32 v0, 0, v0
	v_max_f32_e32 v1, 0, v1
	v_max_f32_e32 v4, 0, v4
	v_max_f32_e32 v5, 0, v5
	v_pk_mul_f32 v[8:9], v[0:1], v[0:1]
	v_max_f32_e32 v0, 0, v6
	v_max_f32_e32 v2, 0, v2
	v_max_f32_e32 v1, 0, v7
	v_max_f32_e32 v3, 0, v3
	v_pk_mul_f32 v[4:5], v[4:5], v[4:5]
	v_pk_mul_f32 v[6:7], v[0:1], v[0:1]
	v_pk_mul_f32 v[10:11], v[2:3], v[2:3]
	v_cvt_pk_bf16_f32 v242, v4, v5
	v_cvt_pk_bf16_f32 v243, v6, v7
	v_cvt_pk_bf16_f32 v244, v8, v9
	v_cvt_pk_bf16_f32 v245, v10, v11
	v_mov_b32_e32 v246, v238
	v_mov_b32_e32 v247, v239
	v_mov_b32_e32 v248, v240
	v_mov_b32_e32 v249, v241
	v_mov_b32_dpp v238, v242 row_shr:8 row_mask:0xf bank_mask:0xc
	v_mov_b32_dpp v239, v243 row_shr:8 row_mask:0xf bank_mask:0xc
	v_mov_b32_dpp v240, v244 row_shr:8 row_mask:0xf bank_mask:0xc
	v_mov_b32_dpp v241, v245 row_shr:8 row_mask:0xf bank_mask:0xc
	global_store_dwordx4 v[18:19], v[238:241], off
	v_lshl_add_u64 v[236:237], v[18:19], 0, vcc
	v_mov_b32_dpp v242, v246 row_shl:8 row_mask:0xf bank_mask:0x3
	v_mov_b32_dpp v243, v247 row_shl:8 row_mask:0xf bank_mask:0x3
	v_mov_b32_dpp v244, v248 row_shl:8 row_mask:0xf bank_mask:0x3
	v_mov_b32_dpp v245, v249 row_shl:8 row_mask:0xf bank_mask:0x3
	global_store_dwordx4 v[236:237], v[242:245], off
	s_and_b64 vcc, exec, s[0:1]
	s_cbranch_vccz .LBB0_763
	s_waitcnt vmcnt(0)
	s_cmpk_gt_u32 s9, 0xff
	s_cbranch_scc1 .LBB0_774
	s_barrier

; #define PG8_STAGE(bufoff, gbase, voff) do { _Pragma("unroll") for (int _i = 0; _i < 2; ++_i) \
;         __builtin_amdgcn_global_load_lds((const unsigned*)((const char*)(gbase) + (voff)[_i]), (LAS unsigned*)(lds + (bufoff) + ldsw + _i * 8192), 16, 0, 0); } while (0)
; #define PG8_LDA(dst, b, h) do { _Pragma("unroll") for (int m = 0; m < 4; ++m) _Pragma("unroll") for (int k = 0; k < 2; ++k) dst[m][k] = *(const LAS bf16x8*)(lds + PG8_SA(b, h) + aoff + m * 2048 + k * 1024); } while (0)
; #define PG8_LDB(dst, b, h) do { _Pragma("unroll") for (int n = 0; n < 2; ++n) _Pragma("unroll") for (int k = 0; k < 2; ++k) dst[n][k] = *(const LAS bf16x8*)(lds + PG8_SB(b, h) + boff + n * 2048 + k * 1024); } while (0)
; #define PG8_MMA(ai, bj, At, Bt) do { __builtin_amdgcn_s_setprio(1); _Pragma("unroll") for (int m = 0; m < 4; ++m) _Pragma("unroll") for (int n = 0; n < 2; ++n) _Pragma("unroll") for (int k = 0; k < 2; ++k) \
;         acc[ai][bj][m][n] = __builtin_amdgcn_mfma_f32_16x16x32_bf16(Bt[n][k], At[m][k], acc[ai][bj][m][n], 0, 0, 0); __builtin_amdgcn_s_setprio(0); } while (0)
; #define PG8_WAIT_V(n) asm volatile("s_waitcnt vmcnt(" #n ")" ::: "memory")
; #define PG8_WAIT_L(n) asm volatile("s_waitcnt lgkmcnt(" #n ")" ::: "memory")
; #define PG8_BAR __builtin_amdgcn_s_barrier()
; #define PG8_SCHED __builtin_amdgcn_sched_barrier(0)
; template <class Epi>
; __device__ __forceinline__ void gemm_phase(LAS unsigned char* lds, const Gemm g, const StaticOrder& S, const Epi& E) {
;     ...
;             PG8_LDB(B0, 0, 0); PG8_SCHED; PG8_LDA(At, 0, 0); PG8_STAGE(PG8_SA(1, 1), a1 + hstepA, voffA);
;             PG8_WAIT_L(8); PG8_BAR; PG8_WAIT_L(0); PG8_MMA(0, 0, At, B0); PG8_BAR; PG8_SCHED;
;             PG8_LDB(B1, 0, 1); PG8_STAGE(PG8_SB(0, 0), b2, voffB);
;             PG8_BAR; PG8_WAIT_L(0); PG8_MMA(0, 1, At, B1); PG8_BAR;
;             PG8_LDA(At, 0, 1); PG8_STAGE(PG8_SA(0, 0), a2, voffA);
;             PG8_BAR; PG8_WAIT_L(0); PG8_MMA(1, 0, At, B0); PG8_BAR; PG8_SCHED;
;             PG8_STAGE(PG8_SB(0, 1), b2 + hstepB, voffB);
;             PG8_WAIT_V(6); PG8_BAR; PG8_MMA(1, 1, At, B1); PG8_BAR;
.LBB0_1204:
	ds_read_b128 v[146:149], v176
	ds_read_b128 v[154:157], v176 offset:1024
	ds_read_b128 v[158:161], v176 offset:2048
	ds_read_b128 v[162:165], v176 offset:3072
	s_add_u32 s22, s20, 0xfffc0080
	s_addc_u32 s23, s21, -1
	s_cmp_eq_u32 s45, 12
	s_cselect_b32 s25, s13, s23
	s_cselect_b32 s24, s41, s22
	s_cselect_b32 s23, s11, s44
	s_cselect_b32 s22, s42, s43
	v_lshl_add_u64 v[150:151], s[20:21], 0, v[138:139]
	s_add_i32 m0, s19, 0xc000
	ds_read_b128 v[166:169], v177
	ds_read_b128 v[170:173], v177 offset:1024
	ds_read_b128 v[180:183], v177 offset:2048
	ds_read_b128 v[184:187], v177 offset:3072
	ds_read_b128 v[188:191], v177 offset:4096
	ds_read_b128 v[192:195], v177 offset:5120
	ds_read_b128 v[196:199], v177 offset:6144
	ds_read_b128 v[200:203], v177 offset:7168
	global_load_lds_dwordx4 v[150:151], off
	v_lshl_add_u64 v[150:151], s[20:21], 0, v[140:141]
	s_add_i32 m0, s19, 0xe000
	s_nop 0
	global_load_lds_dwordx4 v[150:151], off
	s_waitcnt lgkmcnt(8)
	s_barrier
	s_waitcnt lgkmcnt(0)
	s_setprio 1
	s_waitcnt lgkmcnt(0)
	v_mfma_f32_16x16x32_bf16 v[124:127], v[146:149], v[166:169], v[124:127]
	v_mfma_f32_16x16x32_bf16 v[120:123], v[158:161], v[166:169], v[120:123]
	v_mfma_f32_16x16x32_bf16 v[108:111], v[146:149], v[180:183], v[108:111]
	v_mfma_f32_16x16x32_bf16 v[104:107], v[158:161], v[180:183], v[104:107]
	v_mfma_f32_16x16x32_bf16 v[92:95], v[146:149], v[188:191], v[92:95]
	v_mfma_f32_16x16x32_bf16 v[88:91], v[158:161], v[188:191], v[88:91]
	v_mfma_f32_16x16x32_bf16 v[76:79], v[146:149], v[196:199], v[76:79]
	v_mfma_f32_16x16x32_bf16 v[72:75], v[158:161], v[196:199], v[72:75]
	v_mfma_f32_16x16x32_bf16 v[124:127], v[154:157], v[170:173], v[124:127]
	v_mfma_f32_16x16x32_bf16 v[120:123], v[162:165], v[170:173], v[120:123]
	v_mfma_f32_16x16x32_bf16 v[108:111], v[154:157], v[184:187], v[108:111]
	v_mfma_f32_16x16x32_bf16 v[104:107], v[162:165], v[184:187], v[104:107]
	v_mfma_f32_16x16x32_bf16 v[92:95], v[154:157], v[192:195], v[92:95]
	v_mfma_f32_16x16x32_bf16 v[88:91], v[162:165], v[192:195], v[88:91]
	v_mfma_f32_16x16x32_bf16 v[76:79], v[154:157], v[200:203], v[76:79]
	v_mfma_f32_16x16x32_bf16 v[72:75], v[162:165], v[200:203], v[72:75]
	s_setprio 0
	s_barrier
	s_add_i32 s46, s37, s28
	v_lshl_add_u64 v[150:151], s[22:23], 0, v[130:131]
	s_mov_b32 m0, s46
	ds_read_b128 v[204:207], v178
	ds_read_b128 v[208:211], v178 offset:1024
	ds_read_b128 v[212:215], v178 offset:2048
	ds_read_b128 v[216:219], v178 offset:3072
	global_load_lds_dwordx4 v[150:151], off
	v_lshl_add_u64 v[220:221], s[22:23], 0, v[134:135]
	s_add_i32 m0, s46, 0x2000
	s_nop 0
	global_load_lds_dwordx4 v[220:221], off
	s_barrier
	s_waitcnt lgkmcnt(0)
	s_setprio 1
	s_waitcnt lgkmcnt(0)
	v_mfma_f32_16x16x32_bf16 v[116:119], v[204:207], v[166:169], v[116:119]
	v_mfma_f32_16x16x32_bf16 v[112:115], v[212:215], v[166:169], v[112:115]
	v_mfma_f32_16x16x32_bf16 v[100:103], v[204:207], v[180:183], v[100:103]
	v_mfma_f32_16x16x32_bf16 v[96:99], v[212:215], v[180:183], v[96:99]
	v_mfma_f32_16x16x32_bf16 v[84:87], v[204:207], v[188:191], v[84:87]
	v_mfma_f32_16x16x32_bf16 v[80:83], v[212:215], v[188:191], v[80:83]
	v_mfma_f32_16x16x32_bf16 v[68:71], v[204:207], v[196:199], v[68:71]
	v_mfma_f32_16x16x32_bf16 v[64:67], v[212:215], v[196:199], v[64:67]
	v_mfma_f32_16x16x32_bf16 v[116:119], v[208:211], v[170:173], v[116:119]
	v_mfma_f32_16x16x32_bf16 v[112:115], v[216:219], v[170:173], v[112:115]
	v_mfma_f32_16x16x32_bf16 v[100:103], v[208:211], v[184:187], v[100:103]
	v_mfma_f32_16x16x32_bf16 v[96:99], v[216:219], v[184:187], v[96:99]
	v_mfma_f32_16x16x32_bf16 v[84:87], v[208:211], v[192:195], v[84:87]
	v_mfma_f32_16x16x32_bf16 v[80:83], v[216:219], v[192:195], v[80:83]
	v_mfma_f32_16x16x32_bf16 v[68:71], v[208:211], v[200:203], v[68:71]
	v_mfma_f32_16x16x32_bf16 v[64:67], v[216:219], v[200:203], v[64:67]
	s_setprio 0
	s_mov_b32 m0, s19
	v_lshl_add_u64 v[222:223], s[24:25], 0, v[128:129]
	s_barrier
	ds_read_b128 v[166:169], v177 offset:16384
	ds_read_b128 v[170:173], v177 offset:17408
	ds_read_b128 v[180:183], v177 offset:18432
	ds_read_b128 v[184:187], v177 offset:19456
	ds_read_b128 v[188:191], v177 offset:20480
	ds_read_b128 v[192:195], v177 offset:21504
	ds_read_b128 v[196:199], v177 offset:22528
	ds_read_b128 v[200:203], v177 offset:23552
	global_load_lds_dwordx4 v[222:223], off
	v_lshl_add_u64 v[224:225], s[24:25], 0, v[132:133]
	s_mov_b32 m0, s29
	s_nop 0
	global_load_lds_dwordx4 v[224:225], off
	s_barrier
	s_waitcnt lgkmcnt(0)
	s_setprio 1
	s_waitcnt lgkmcnt(0)
	v_mfma_f32_16x16x32_bf16 v[60:63], v[146:149], v[166:169], v[60:63]
	v_mfma_f32_16x16x32_bf16 v[56:59], v[158:161], v[166:169], v[56:59]
	v_mfma_f32_16x16x32_bf16 v[44:47], v[146:149], v[180:183], v[44:47]
	v_mfma_f32_16x16x32_bf16 v[40:43], v[158:161], v[180:183], v[40:43]
	v_mfma_f32_16x16x32_bf16 v[28:31], v[146:149], v[188:191], v[28:31]
	v_mfma_f32_16x16x32_bf16 v[24:27], v[158:161], v[188:191], v[24:27]
	v_mfma_f32_16x16x32_bf16 v[12:15], v[146:149], v[196:199], v[12:15]
	v_mfma_f32_16x16x32_bf16 v[8:11], v[158:161], v[196:199], v[8:11]
	v_mfma_f32_16x16x32_bf16 v[60:63], v[154:157], v[170:173], v[60:63]
	v_mfma_f32_16x16x32_bf16 v[56:59], v[162:165], v[170:173], v[56:59]
	v_mfma_f32_16x16x32_bf16 v[44:47], v[154:157], v[184:187], v[44:47]
	v_mfma_f32_16x16x32_bf16 v[40:43], v[162:165], v[184:187], v[40:43]
	v_mfma_f32_16x16x32_bf16 v[28:31], v[154:157], v[192:195], v[28:31]
	v_mfma_f32_16x16x32_bf16 v[24:27], v[162:165], v[192:195], v[24:27]
	v_mfma_f32_16x16x32_bf16 v[12:15], v[154:157], v[200:203], v[12:15]
	v_mfma_f32_16x16x32_bf16 v[8:11], v[162:165], v[200:203], v[8:11]
	s_setprio 0
	s_barrier
; #define PG8_STAGE(bufoff, gbase, voff) do { _Pragma("unroll") for (int _i = 0; _i < 2; ++_i) \
;         __builtin_amdgcn_global_load_lds((const unsigned*)((const char*)(gbase) + (voff)[_i]), (LAS unsigned*)(lds + (bufoff) + ldsw + _i * 8192), 16, 0, 0); } while (0)
; #define PG8_LDA(dst, b, h) do { _Pragma("unroll") for (int m = 0; m < 4; ++m) _Pragma("unroll") for (int k = 0; k < 2; ++k) dst[m][k] = *(const LAS bf16x8*)(lds + PG8_SA(b, h) + aoff + m * 2048 + k * 1024); } while (0)
; #define PG8_LDB(dst, b, h) do { _Pragma("unroll") for (int n = 0; n < 2; ++n) _Pragma("unroll") for (int k = 0; k < 2; ++k) dst[n][k] = *(const LAS bf16x8*)(lds + PG8_SB(b, h) + boff + n * 2048 + k * 1024); } while (0)
; #define PG8_MMA(ai, bj, At, Bt) do { __builtin_amdgcn_s_setprio(1); _Pragma("unroll") for (int m = 0; m < 4; ++m) _Pragma("unroll") for (int n = 0; n < 2; ++n) _Pragma("unroll") for (int k = 0; k < 2; ++k) \
;         acc[ai][bj][m][n] = __builtin_amdgcn_mfma_f32_16x16x32_bf16(Bt[n][k], At[m][k], acc[ai][bj][m][n], 0, 0, 0); __builtin_amdgcn_s_setprio(0); } while (0)
; #define PG8_WAIT_V(n) asm volatile("s_waitcnt vmcnt(" #n ")" ::: "memory")
; #define PG8_WAIT_L(n) asm volatile("s_waitcnt lgkmcnt(" #n ")" ::: "memory")
; #define PG8_BAR __builtin_amdgcn_s_barrier()
; #define PG8_SCHED __builtin_amdgcn_sched_barrier(0)
; template <class Epi>
; __device__ __forceinline__ void gemm_phase(LAS unsigned char* lds, const Gemm g, const StaticOrder& S, const Epi& E) {
;     ...
;             PG8_WAIT_V(6); PG8_BAR; PG8_MMA(1, 1, At, B1); PG8_BAR;
;             PG8_LDB(B0, 1, 0); PG8_SCHED; PG8_LDA(At, 1, 0); PG8_STAGE(PG8_SA(0, 1), a2 + hstepA, voffA);
;             PG8_WAIT_L(8); PG8_BAR; PG8_WAIT_L(0); PG8_MMA(0, 0, At, B0); PG8_BAR; PG8_SCHED;
;             PG8_LDB(B1, 1, 1); PG8_STAGE(PG8_SB(1, 0), b3, voffB);
;             PG8_BAR; PG8_WAIT_L(0); PG8_MMA(0, 1, At, B1); PG8_BAR;
;             PG8_LDA(At, 1, 1); PG8_STAGE(PG8_SA(1, 0), a3, voffA);
;             PG8_BAR; PG8_WAIT_L(0); PG8_MMA(1, 0, At, B0); PG8_BAR; PG8_SCHED;
	s_add_u32 s46, s22, 0x40000
	s_addc_u32 s47, s23, 0
	s_add_i32 s48, s38, s28
	v_lshl_add_u64 v[146:147], s[46:47], 0, v[130:131]
	s_mov_b32 m0, s48
	s_nop 0
	global_load_lds_dwordx4 v[146:147], off
	v_lshl_add_u64 v[146:147], s[46:47], 0, v[134:135]
	s_add_i32 m0, s48, 0x2000
	s_nop 0
	global_load_lds_dwordx4 v[146:147], off
	s_waitcnt vmcnt(6)
	s_barrier
	s_setprio 1
	v_mfma_f32_16x16x32_bf16 v[52:55], v[204:207], v[166:169], v[52:55]
	v_mfma_f32_16x16x32_bf16 v[48:51], v[212:215], v[166:169], v[48:51]
	v_mfma_f32_16x16x32_bf16 v[36:39], v[204:207], v[180:183], v[36:39]
	v_mfma_f32_16x16x32_bf16 v[32:35], v[212:215], v[180:183], v[32:35]
	v_mfma_f32_16x16x32_bf16 v[20:23], v[204:207], v[188:191], v[20:23]
	v_mfma_f32_16x16x32_bf16 v[16:19], v[212:215], v[188:191], v[16:19]
	v_mfma_f32_16x16x32_bf16 v[4:7], v[204:207], v[196:199], v[4:7]
	v_mfma_f32_16x16x32_bf16 v[0:3], v[212:215], v[196:199], v[0:3]
	v_mfma_f32_16x16x32_bf16 v[52:55], v[208:211], v[170:173], v[52:55]
	v_mfma_f32_16x16x32_bf16 v[48:51], v[216:219], v[170:173], v[48:51]
	v_mfma_f32_16x16x32_bf16 v[36:39], v[208:211], v[184:187], v[36:39]
	v_mfma_f32_16x16x32_bf16 v[32:35], v[216:219], v[184:187], v[32:35]
	v_mfma_f32_16x16x32_bf16 v[20:23], v[208:211], v[192:195], v[20:23]
	v_mfma_f32_16x16x32_bf16 v[16:19], v[216:219], v[192:195], v[16:19]
	v_mfma_f32_16x16x32_bf16 v[4:7], v[208:211], v[200:203], v[4:7]
	v_mfma_f32_16x16x32_bf16 v[0:3], v[216:219], v[200:203], v[0:3]
	s_setprio 0
	s_add_i32 s46, 0, 0x18000
	v_add_u32_e32 v162, s46, v174
	s_barrier
	ds_read_b128 v[146:149], v162
	ds_read_b128 v[154:157], v162 offset:1024
	ds_read_b128 v[158:161], v162 offset:2048
	ds_read_b128 v[162:165], v162 offset:3072
	s_add_u32 s24, s24, 0x40000
	s_addc_u32 s25, s25, 0
	s_mov_b32 m0, s30
	v_lshl_add_u64 v[204:205], s[24:25], 0, v[128:129]
	ds_read_b128 v[166:169], v177 offset:32768
	ds_read_b128 v[170:173], v177 offset:33792
	ds_read_b128 v[180:183], v177 offset:34816
	ds_read_b128 v[184:187], v177 offset:35840
	ds_read_b128 v[188:191], v177 offset:36864
	ds_read_b128 v[192:195], v177 offset:37888
	ds_read_b128 v[196:199], v177 offset:38912
	ds_read_b128 v[200:203], v177 offset:39936
	global_load_lds_dwordx4 v[204:205], off
	v_lshl_add_u64 v[204:205], s[24:25], 0, v[132:133]
	s_mov_b32 m0, s31
	s_nop 0
	global_load_lds_dwordx4 v[204:205], off
	s_waitcnt lgkmcnt(8)
	s_barrier
	s_waitcnt lgkmcnt(0)
	s_setprio 1
	s_waitcnt lgkmcnt(0)
	v_mfma_f32_16x16x32_bf16 v[124:127], v[146:149], v[166:169], v[124:127]
	v_mfma_f32_16x16x32_bf16 v[120:123], v[158:161], v[166:169], v[120:123]
	v_mfma_f32_16x16x32_bf16 v[108:111], v[146:149], v[180:183], v[108:111]
	v_mfma_f32_16x16x32_bf16 v[104:107], v[158:161], v[180:183], v[104:107]
	v_mfma_f32_16x16x32_bf16 v[92:95], v[146:149], v[188:191], v[92:95]
	v_mfma_f32_16x16x32_bf16 v[88:91], v[158:161], v[188:191], v[88:91]
	v_mfma_f32_16x16x32_bf16 v[76:79], v[146:149], v[196:199], v[76:79]
	v_mfma_f32_16x16x32_bf16 v[72:75], v[158:161], v[196:199], v[72:75]
	v_mfma_f32_16x16x32_bf16 v[124:127], v[154:157], v[170:173], v[124:127]
	v_mfma_f32_16x16x32_bf16 v[120:123], v[162:165], v[170:173], v[120:123]
	v_mfma_f32_16x16x32_bf16 v[108:111], v[154:157], v[184:187], v[108:111]
	v_mfma_f32_16x16x32_bf16 v[104:107], v[162:165], v[184:187], v[104:107]
	v_mfma_f32_16x16x32_bf16 v[92:95], v[154:157], v[192:195], v[92:95]
	v_mfma_f32_16x16x32_bf16 v[88:91], v[162:165], v[192:195], v[88:91]
	v_mfma_f32_16x16x32_bf16 v[76:79], v[154:157], v[200:203], v[76:79]
	v_mfma_f32_16x16x32_bf16 v[72:75], v[162:165], v[200:203], v[72:75]
	s_setprio 0
	s_barrier
	s_add_i32 s24, 0, 0x1c000
	s_add_i32 s25, s46, s28
	v_add_u32_e32 v216, s24, v174
	v_lshl_add_u64 v[150:151], v[150:151], 0, s[4:5]
	s_mov_b32 m0, s25
	ds_read_b128 v[204:207], v216
	ds_read_b128 v[208:211], v216 offset:1024
	ds_read_b128 v[212:215], v216 offset:2048
	ds_read_b128 v[216:219], v216 offset:3072
	global_load_lds_dwordx4 v[150:151], off
	v_lshl_add_u64 v[150:151], v[220:221], 0, s[4:5]
	s_add_i32 m0, s25, 0x2000
	s_nop 0
	global_load_lds_dwordx4 v[150:151], off
	s_barrier
	s_waitcnt lgkmcnt(0)
	s_setprio 1
	s_waitcnt lgkmcnt(0)
	v_mfma_f32_16x16x32_bf16 v[116:119], v[204:207], v[166:169], v[116:119]
	v_mfma_f32_16x16x32_bf16 v[112:115], v[212:215], v[166:169], v[112:115]
	v_mfma_f32_16x16x32_bf16 v[100:103], v[204:207], v[180:183], v[100:103]
	v_mfma_f32_16x16x32_bf16 v[96:99], v[212:215], v[180:183], v[96:99]
	v_mfma_f32_16x16x32_bf16 v[84:87], v[204:207], v[188:191], v[84:87]
	v_mfma_f32_16x16x32_bf16 v[80:83], v[212:215], v[188:191], v[80:83]
	v_mfma_f32_16x16x32_bf16 v[68:71], v[204:207], v[196:199], v[68:71]
	v_mfma_f32_16x16x32_bf16 v[64:67], v[212:215], v[196:199], v[64:67]
	v_mfma_f32_16x16x32_bf16 v[116:119], v[208:211], v[170:173], v[116:119]
	v_mfma_f32_16x16x32_bf16 v[112:115], v[216:219], v[170:173], v[112:115]
	v_mfma_f32_16x16x32_bf16 v[100:103], v[208:211], v[184:187], v[100:103]
	v_mfma_f32_16x16x32_bf16 v[96:99], v[216:219], v[184:187], v[96:99]
	v_mfma_f32_16x16x32_bf16 v[84:87], v[208:211], v[192:195], v[84:87]
	v_mfma_f32_16x16x32_bf16 v[80:83], v[216:219], v[192:195], v[80:83]
	v_mfma_f32_16x16x32_bf16 v[68:71], v[208:211], v[200:203], v[68:71]
	v_mfma_f32_16x16x32_bf16 v[64:67], v[216:219], v[200:203], v[64:67]
	s_setprio 0
	s_mov_b32 m0, s34
	v_lshl_add_u64 v[150:151], v[222:223], 0, s[4:5]
	s_barrier
	ds_read_b128 v[166:169], v177 offset:49152
	ds_read_b128 v[170:173], v177 offset:50176
	ds_read_b128 v[180:183], v177 offset:51200
	ds_read_b128 v[184:187], v177 offset:52224
	ds_read_b128 v[188:191], v177 offset:53248
	ds_read_b128 v[192:195], v177 offset:54272
	ds_read_b128 v[196:199], v177 offset:55296
	ds_read_b128 v[200:203], v177 offset:56320
	global_load_lds_dwordx4 v[150:151], off
	v_lshl_add_u64 v[150:151], v[224:225], 0, s[4:5]
	s_mov_b32 m0, s35
	s_nop 0
	global_load_lds_dwordx4 v[150:151], off
	s_barrier
; #define PG8_STAGE(bufoff, gbase, voff) do { _Pragma("unroll") for (int _i = 0; _i < 2; ++_i) \
;         __builtin_amdgcn_global_load_lds((const unsigned*)((const char*)(gbase) + (voff)[_i]), (LAS unsigned*)(lds + (bufoff) + ldsw + _i * 8192), 16, 0, 0); } while (0)
; #define PG8_MMA(ai, bj, At, Bt) do { __builtin_amdgcn_s_setprio(1); _Pragma("unroll") for (int m = 0; m < 4; ++m) _Pragma("unroll") for (int n = 0; n < 2; ++n) _Pragma("unroll") for (int k = 0; k < 2; ++k) \
;         acc[ai][bj][m][n] = __builtin_amdgcn_mfma_f32_16x16x32_bf16(Bt[n][k], At[m][k], acc[ai][bj][m][n], 0, 0, 0); __builtin_amdgcn_s_setprio(0); } while (0)
; #define PG8_WAIT_V(n) asm volatile("s_waitcnt vmcnt(" #n ")" ::: "memory")
; #define PG8_WAIT_L(n) asm volatile("s_waitcnt lgkmcnt(" #n ")" ::: "memory")
; #define PG8_BAR __builtin_amdgcn_s_barrier()
; #define PG8_SCHED __builtin_amdgcn_sched_barrier(0)
;     __device__ __forceinline__ void operator()(const f32x4 (&acc)[2][2][4][2], const Unit& u, int wr, int wc, int fr, int fq, const float (&)[8]) const {
;     ...
;         const int col0 = u.pn * BM + wc * 32 + 8 * fq;
; #pragma unroll
;         for (int ai = 0; ai < 2; ++ai)
; #pragma unroll
;             for (int m = 0; m < 4; ++m) { const int row = row0 + ai * HALF + m * 16; const float rs = rsqrtf(ep[ai * 4 + m] * (1.0f / 1024.0f) + EPS);
;                 u16* rowp = O + (size_t)row * ldc + col0;
; template <class Epi>
; __device__ __forceinline__ void gemm_phase(LAS unsigned char* lds, const Gemm g, const StaticOrder& S, const Epi& E) {
;     ...
;             PG8_BAR; PG8_WAIT_L(0); PG8_MMA(1, 0, At, B0); PG8_BAR; PG8_SCHED;
;             PG8_STAGE(PG8_SB(1, 1), b3 + hstepB, voffB);
;             PG8_WAIT_V(6); PG8_BAR; PG8_MMA(1, 1, At, B1); PG8_BAR;
;         }
;         E(acc, cur, wr, wc, fr, fq, epre);
;         if (!has_next) break;
	s_waitcnt lgkmcnt(0)
	s_setprio 1
	s_waitcnt lgkmcnt(0)
	v_mfma_f32_16x16x32_bf16 v[60:63], v[146:149], v[166:169], v[60:63]
	v_mfma_f32_16x16x32_bf16 v[56:59], v[158:161], v[166:169], v[56:59]
	v_mfma_f32_16x16x32_bf16 v[44:47], v[146:149], v[180:183], v[44:47]
	v_mfma_f32_16x16x32_bf16 v[40:43], v[158:161], v[180:183], v[40:43]
	v_mfma_f32_16x16x32_bf16 v[28:31], v[146:149], v[188:191], v[28:31]
	v_mfma_f32_16x16x32_bf16 v[24:27], v[158:161], v[188:191], v[24:27]
	v_mfma_f32_16x16x32_bf16 v[12:15], v[146:149], v[196:199], v[12:15]
	v_mfma_f32_16x16x32_bf16 v[8:11], v[158:161], v[196:199], v[8:11]
	v_mfma_f32_16x16x32_bf16 v[60:63], v[154:157], v[170:173], v[60:63]
	v_mfma_f32_16x16x32_bf16 v[56:59], v[162:165], v[170:173], v[56:59]
	v_mfma_f32_16x16x32_bf16 v[44:47], v[154:157], v[184:187], v[44:47]
	v_mfma_f32_16x16x32_bf16 v[40:43], v[162:165], v[184:187], v[40:43]
	v_mfma_f32_16x16x32_bf16 v[28:31], v[154:157], v[192:195], v[28:31]
	v_mfma_f32_16x16x32_bf16 v[24:27], v[162:165], v[192:195], v[24:27]
	v_mfma_f32_16x16x32_bf16 v[12:15], v[154:157], v[200:203], v[12:15]
	v_mfma_f32_16x16x32_bf16 v[8:11], v[162:165], v[200:203], v[8:11]
	s_setprio 0
	s_barrier
	s_add_u32 s22, s22, 0x40080
	s_addc_u32 s23, s23, 0
	s_add_i32 s24, s24, s28
	v_lshl_add_u64 v[146:147], s[22:23], 0, v[130:131]
	s_mov_b32 m0, s24
	s_nop 0
	global_load_lds_dwordx4 v[146:147], off
	v_lshl_add_u64 v[146:147], s[22:23], 0, v[134:135]
	s_add_i32 m0, s24, 0x2000
	s_nop 0
	global_load_lds_dwordx4 v[146:147], off
	s_waitcnt vmcnt(6)
	s_barrier
	s_setprio 1
	v_mfma_f32_16x16x32_bf16 v[52:55], v[204:207], v[166:169], v[52:55]
	v_mfma_f32_16x16x32_bf16 v[48:51], v[212:215], v[166:169], v[48:51]
	v_mfma_f32_16x16x32_bf16 v[36:39], v[204:207], v[180:183], v[36:39]
	v_mfma_f32_16x16x32_bf16 v[32:35], v[212:215], v[180:183], v[32:35]
	v_mfma_f32_16x16x32_bf16 v[20:23], v[204:207], v[188:191], v[20:23]
	v_mfma_f32_16x16x32_bf16 v[16:19], v[212:215], v[188:191], v[16:19]
	v_mfma_f32_16x16x32_bf16 v[4:7], v[204:207], v[196:199], v[4:7]
	v_mfma_f32_16x16x32_bf16 v[0:3], v[212:215], v[196:199], v[0:3]
	v_mfma_f32_16x16x32_bf16 v[52:55], v[208:211], v[170:173], v[52:55]
	v_mfma_f32_16x16x32_bf16 v[48:51], v[216:219], v[170:173], v[48:51]
	v_mfma_f32_16x16x32_bf16 v[36:39], v[208:211], v[184:187], v[36:39]
	v_mfma_f32_16x16x32_bf16 v[32:35], v[216:219], v[184:187], v[32:35]
	v_mfma_f32_16x16x32_bf16 v[20:23], v[208:211], v[192:195], v[20:23]
	v_mfma_f32_16x16x32_bf16 v[16:19], v[216:219], v[192:195], v[16:19]
	v_mfma_f32_16x16x32_bf16 v[4:7], v[208:211], v[200:203], v[4:7]
	v_mfma_f32_16x16x32_bf16 v[0:3], v[216:219], v[200:203], v[0:3]
	s_setprio 0
	s_add_i32 s45, s45, 2
	s_add_u32 s20, s20, 0x100
	s_addc_u32 s21, s21, 0
	s_add_u32 s43, s43, 0x100
	s_addc_u32 s44, s44, 0
	s_cmp_gt_u32 s45, 13
	s_barrier
	s_cbranch_scc0 .LBB0_1204
	s_bfe_u32 vcc_lo, s18, 0x20003
	s_lshl_b32 vcc_lo, vcc_lo, 10
	s_add_i32 vcc_lo, vcc_lo, 0x20010
	v_lshl_add_u32 v236, v153, 2, vcc_lo
	ds_read_b32 v228, v236
	ds_read_b32 v229, v236 offset:64
	ds_read_b32 v230, v236 offset:128
	ds_read_b32 v231, v236 offset:192
	ds_read_b32 v232, v236 offset:512
	ds_read_b32 v233, v236 offset:576
	ds_read_b32 v234, v236 offset:640
	ds_read_b32 v235, v236 offset:704
	s_waitcnt lgkmcnt(0)
	v_lshl_add_u32 v148, s18, 8, v153
	v_and_b32_e32 v236, 8, v153
	v_sub_u32_e32 v148, v148, v236
	s_mov_b32 vcc_lo, 0x10000
	s_mov_b32 vcc_hi, 0
	v_ashrrev_i32_e32 v149, 31, v148
	v_or_b32_e32 v172, 16, v148
	v_ashrrev_i32_e32 v173, 31, v172
	v_or_b32_e32 v168, 32, v148
	v_or_b32_e32 v164, 48, v148
	v_ashrrev_i32_e32 v169, 31, v168
	v_ashrrev_i32_e32 v165, 31, v164
	v_add_u32_e32 v162, 0x80, v148
	v_add_u32_e32 v156, 0x90, v148
	v_ashrrev_i32_e32 v163, 31, v162
	v_ashrrev_i32_e32 v157, 31, v156
	v_add_u32_e32 v150, 0xa0, v148
	v_ashrrev_i32_e32 v151, 31, v150
	v_add_u32_e32 v146, 0xb0, v148
	v_ashrrev_i32_e32 v147, 31, v146
	v_and_b32_e32 v237, 0x60, v175
	v_lshlrev_b32_e32 v237, 1, v237
	v_and_b32_e32 v238, 0x18, v175
	v_or_b32_e32 v237, v237, v238
	v_lshl_or_b32 v237, v236, 2, v237
	v_lshl_or_b32 v166, s40, 8, v237
	v_ashrrev_i32_e32 v167, 31, v166
	v_lshlrev_b64 v[170:171], 13, v[148:149]
	v_lshlrev_b64 v[148:149], 1, v[166:167]
	v_lshl_add_u64 v[166:167], s[96:97], 0, v[170:171]
	v_lshl_add_u64 v[210:211], v[166:167], 0, v[148:149]
	s_mov_b32 s40, s10
	s_mov_b32 s18, s12
	s_mov_b64 s[22:23], s[16:17]
	s_mov_b64 s[20:21], s[14:15]
	s_waitcnt vmcnt(8)
	s_waitcnt lgkmcnt(0)
	s_waitcnt lgkmcnt(0)
; __device__ __forceinline__ unsigned pk2(float lo, float hi) { const f32x2 v = (f32x2){lo, hi}; const bf16x2_t b = __builtin_convertvector(v, bf16x2_t); return __builtin_bit_cast(unsigned, b); }
;     __device__ __forceinline__ void operator()(const f32x4 (&acc)[2][2][4][2], const Unit& u, int wr, int wc, int fr, int fq, const float (&)[8]) const {
;     ...
;             for (int m = 0; m < 4; ++m) { const int row = row0 + ai * HALF + m * 16; const float rs = rsqrtf(ep[ai * 4 + m] * (1.0f / 1024.0f) + EPS);
;                 u16* rowp = O + (size_t)row * ldc + col0;
; #pragma unroll
;                 for (int bj = 0; bj < 2; ++bj) { f32x4 v0 = acc[ai][bj][m][0] * rs, v1 = acc[ai][bj][m][1] * rs;
;                     if (ACT == 1) {
; #pragma unroll
;                         for (int j = 0; j < 4; ++j) { const float a0 = fmaxf(v0[j], 0.f), a1 = fmaxf(v1[j], 0.f); v0[j] = a0 * a0; v1[j] = a1 * a1; } }
;                     u32x4 w; w.x = pk2(v0[0], v0[1]); w.y = pk2(v0[2], v0[3]); w.z = pk2(v1[0], v1[1]); w.w = pk2(v1[2], v1[3]);
;                     *(u32x4*)(rowp + bj * HALF) = w; } }
	v_mov_b32_e32 v182, v228
	v_pk_mul_f32 v[120:121], v[120:121], v[182:183] op_sel_hi:[1,0]
	v_pk_mul_f32 v[126:127], v[126:127], v[182:183] op_sel_hi:[1,0]
	v_pk_mul_f32 v[124:125], v[124:125], v[182:183] op_sel_hi:[1,0]
	v_pk_mul_f32 v[122:123], v[122:123], v[182:183] op_sel_hi:[1,0]
	v_max_f32_e32 v120, 0, v120
	v_max_f32_e32 v121, 0, v121
	v_max_f32_e32 v124, 0, v124
	v_max_f32_e32 v125, 0, v125
	v_pk_mul_f32 v[188:189], v[120:121], v[120:121]
	v_max_f32_e32 v120, 0, v126
	v_max_f32_e32 v122, 0, v122
	v_max_f32_e32 v121, 0, v127
	v_max_f32_e32 v123, 0, v123
	v_pk_mul_f32 v[124:125], v[124:125], v[124:125]
	v_pk_mul_f32 v[126:127], v[120:121], v[120:121]
	v_pk_mul_f32 v[192:193], v[122:123], v[122:123]
	v_pk_mul_f32 v[114:115], v[114:115], v[182:183] op_sel_hi:[1,0]
	v_cvt_pk_bf16_f32 v238, v124, v125
	v_cvt_pk_bf16_f32 v239, v126, v127
	v_cvt_pk_bf16_f32 v240, v188, v189
	v_cvt_pk_bf16_f32 v241, v192, v193
	v_pk_mul_f32 v[116:117], v[116:117], v[182:183] op_sel_hi:[1,0]
	v_pk_mul_f32 v[112:113], v[112:113], v[182:183] op_sel_hi:[1,0]
	v_max_f32_e32 v114, 0, v114
	v_max_f32_e32 v115, 0, v115
	v_pk_mul_f32 v[118:119], v[118:119], v[182:183] op_sel_hi:[1,0]
	v_max_f32_e32 v116, 0, v116
	v_max_f32_e32 v112, 0, v112
	v_max_f32_e32 v117, 0, v117
	v_max_f32_e32 v113, 0, v113
	v_pk_mul_f32 v[122:123], v[114:115], v[114:115]
	v_pk_mul_f32 v[116:117], v[116:117], v[116:117]
	v_pk_mul_f32 v[120:121], v[112:113], v[112:113]
	v_max_f32_e32 v112, 0, v118
	v_max_f32_e32 v113, 0, v119
	v_pk_mul_f32 v[118:119], v[112:113], v[112:113]
	v_cvt_pk_bf16_f32 v242, v116, v117
	v_cvt_pk_bf16_f32 v243, v118, v119
	v_cvt_pk_bf16_f32 v244, v120, v121
	v_cvt_pk_bf16_f32 v245, v122, v123
	v_mov_b32_e32 v246, v238
	v_mov_b32_e32 v247, v239
	v_mov_b32_e32 v248, v240
	v_mov_b32_e32 v249, v241
	v_mov_b32_dpp v238, v242 row_shr:8 row_mask:0xf bank_mask:0xc
	v_mov_b32_dpp v239, v243 row_shr:8 row_mask:0xf bank_mask:0xc
	v_mov_b32_dpp v240, v244 row_shr:8 row_mask:0xf bank_mask:0xc
	v_mov_b32_dpp v241, v245 row_shr:8 row_mask:0xf bank_mask:0xc
	global_store_dwordx4 v[210:211], v[238:241], off
	v_lshl_add_u64 v[236:237], v[210:211], 0, vcc
	v_mov_b32_dpp v242, v246 row_shl:8 row_mask:0xf bank_mask:0x3
	v_mov_b32_dpp v243, v247 row_shl:8 row_mask:0xf bank_mask:0x3
	v_mov_b32_dpp v244, v248 row_shl:8 row_mask:0xf bank_mask:0x3
	v_mov_b32_dpp v245, v249 row_shl:8 row_mask:0xf bank_mask:0x3
	global_store_dwordx4 v[236:237], v[242:245], off
	s_nop 1
	v_mov_b32_e32 v112, v229
	v_pk_mul_f32 v[104:105], v[104:105], v[112:113] op_sel_hi:[1,0]
	v_pk_mul_f32 v[110:111], v[110:111], v[112:113] op_sel_hi:[1,0]
	v_pk_mul_f32 v[108:109], v[108:109], v[112:113] op_sel_hi:[1,0]
	v_pk_mul_f32 v[106:107], v[106:107], v[112:113] op_sel_hi:[1,0]
	v_max_f32_e32 v104, 0, v104
	v_max_f32_e32 v105, 0, v105
	v_lshlrev_b64 v[114:115], 13, v[172:173]
	v_max_f32_e32 v108, 0, v108
	v_max_f32_e32 v109, 0, v109
	v_pk_mul_f32 v[116:117], v[104:105], v[104:105]
	v_max_f32_e32 v104, 0, v110
	v_max_f32_e32 v106, 0, v106
	v_max_f32_e32 v105, 0, v111
	v_max_f32_e32 v107, 0, v107
	v_lshl_add_u64 v[114:115], s[96:97], 0, v[114:115]
	v_pk_mul_f32 v[108:109], v[108:109], v[108:109]
	v_pk_mul_f32 v[110:111], v[104:105], v[104:105]
	v_pk_mul_f32 v[118:119], v[106:107], v[106:107]
	v_pk_mul_f32 v[96:97], v[96:97], v[112:113] op_sel_hi:[1,0]
	v_lshl_add_u64 v[114:115], v[114:115], 0, v[148:149]
	v_cvt_pk_bf16_f32 v238, v108, v109
	v_cvt_pk_bf16_f32 v239, v110, v111
	v_cvt_pk_bf16_f32 v240, v116, v117
	v_cvt_pk_bf16_f32 v241, v118, v119
	v_pk_mul_f32 v[102:103], v[102:103], v[112:113] op_sel_hi:[1,0]
	v_max_f32_e32 v96, 0, v96
	v_max_f32_e32 v97, 0, v97
	v_pk_mul_f32 v[100:101], v[100:101], v[112:113] op_sel_hi:[1,0]
	v_pk_mul_f32 v[98:99], v[98:99], v[112:113] op_sel_hi:[1,0]
	v_pk_mul_f32 v[104:105], v[96:97], v[96:97]
	v_max_f32_e32 v96, 0, v102
	v_max_f32_e32 v97, 0, v103
	v_max_f32_e32 v100, 0, v100
	v_max_f32_e32 v101, 0, v101
	v_pk_mul_f32 v[100:101], v[100:101], v[100:101]
	v_pk_mul_f32 v[108:109], v[96:97], v[96:97]
	v_cvt_pk_bf16_f32 v242, v100, v101
	s_waitcnt lgkmcnt(0)
	v_max_f32_e32 v98, 0, v98
	v_max_f32_e32 v99, 0, v99
	v_pk_mul_f32 v[110:111], v[98:99], v[98:99]
	v_cvt_pk_bf16_f32 v243, v108, v109
	v_cvt_pk_bf16_f32 v244, v104, v105
	v_cvt_pk_bf16_f32 v245, v110, v111
	v_mov_b32_e32 v246, v238
	v_mov_b32_e32 v247, v239
	v_mov_b32_e32 v248, v240
	v_mov_b32_e32 v249, v241
	v_mov_b32_dpp v238, v242 row_shr:8 row_mask:0xf bank_mask:0xc
	v_mov_b32_dpp v239, v243 row_shr:8 row_mask:0xf bank_mask:0xc
	v_mov_b32_dpp v240, v244 row_shr:8 row_mask:0xf bank_mask:0xc
	v_mov_b32_dpp v241, v245 row_shr:8 row_mask:0xf bank_mask:0xc
	global_store_dwordx4 v[114:115], v[238:241], off
	v_lshl_add_u64 v[236:237], v[114:115], 0, vcc
	v_mov_b32_dpp v242, v246 row_shl:8 row_mask:0xf bank_mask:0x3
	v_mov_b32_dpp v243, v247 row_shl:8 row_mask:0xf bank_mask:0x3
	v_mov_b32_dpp v244, v248 row_shl:8 row_mask:0xf bank_mask:0x3
	v_mov_b32_dpp v245, v249 row_shl:8 row_mask:0xf bank_mask:0x3
	global_store_dwordx4 v[236:237], v[242:245], off
	s_waitcnt lgkmcnt(0)
; __device__ __forceinline__ unsigned pk2(float lo, float hi) { const f32x2 v = (f32x2){lo, hi}; const bf16x2_t b = __builtin_convertvector(v, bf16x2_t); return __builtin_bit_cast(unsigned, b); }
;     __device__ __forceinline__ void operator()(const f32x4 (&acc)[2][2][4][2], const Unit& u, int wr, int wc, int fr, int fq, const float (&)[8]) const {
;     ...
;             for (int m = 0; m < 4; ++m) { const int row = row0 + ai * HALF + m * 16; const float rs = rsqrtf(ep[ai * 4 + m] * (1.0f / 1024.0f) + EPS);
;                 u16* rowp = O + (size_t)row * ldc + col0;
; #pragma unroll
;                 for (int bj = 0; bj < 2; ++bj) { f32x4 v0 = acc[ai][bj][m][0] * rs, v1 = acc[ai][bj][m][1] * rs;
;                     if (ACT == 1) {
; #pragma unroll
;                         for (int j = 0; j < 4; ++j) { const float a0 = fmaxf(v0[j], 0.f), a1 = fmaxf(v1[j], 0.f); v0[j] = a0 * a0; v1[j] = a1 * a1; } }
;                     u32x4 w; w.x = pk2(v0[0], v0[1]); w.y = pk2(v0[2], v0[3]); w.z = pk2(v1[0], v1[1]); w.w = pk2(v1[2], v1[3]);
;                     *(u32x4*)(rowp + bj * HALF) = w; } }
	s_nop 0
	s_nop 0
	s_nop 0
	s_nop 1
	v_lshlrev_b64 v[98:99], 13, v[168:169]
	v_lshl_add_u64 v[98:99], s[96:97], 0, v[98:99]
	v_lshl_add_u64 v[98:99], v[98:99], 0, v[148:149]
	v_mov_b32_e32 v100, v230
	v_pk_mul_f32 v[88:89], v[88:89], v[100:101] op_sel_hi:[1,0]
	v_pk_mul_f32 v[94:95], v[94:95], v[100:101] op_sel_hi:[1,0]
	v_pk_mul_f32 v[92:93], v[92:93], v[100:101] op_sel_hi:[1,0]
	v_pk_mul_f32 v[90:91], v[90:91], v[100:101] op_sel_hi:[1,0]
	v_max_f32_e32 v88, 0, v88
	v_max_f32_e32 v89, 0, v89
	v_max_f32_e32 v92, 0, v92
	v_max_f32_e32 v93, 0, v93
	v_pk_mul_f32 v[102:103], v[88:89], v[88:89]
	v_max_f32_e32 v88, 0, v94
	v_max_f32_e32 v90, 0, v90
	v_max_f32_e32 v89, 0, v95
	v_max_f32_e32 v91, 0, v91
	v_pk_mul_f32 v[92:93], v[92:93], v[92:93]
	v_pk_mul_f32 v[94:95], v[88:89], v[88:89]
	v_pk_mul_f32 v[104:105], v[90:91], v[90:91]
	v_pk_mul_f32 v[82:83], v[82:83], v[100:101] op_sel_hi:[1,0]
	v_cvt_pk_bf16_f32 v238, v92, v93
	v_cvt_pk_bf16_f32 v239, v94, v95
	v_cvt_pk_bf16_f32 v240, v102, v103
	v_cvt_pk_bf16_f32 v241, v104, v105
	v_pk_mul_f32 v[84:85], v[84:85], v[100:101] op_sel_hi:[1,0]
	v_pk_mul_f32 v[80:81], v[80:81], v[100:101] op_sel_hi:[1,0]
	v_max_f32_e32 v82, 0, v82
	v_max_f32_e32 v83, 0, v83
	v_pk_mul_f32 v[86:87], v[86:87], v[100:101] op_sel_hi:[1,0]
	v_max_f32_e32 v84, 0, v84
	v_max_f32_e32 v80, 0, v80
	v_max_f32_e32 v85, 0, v85
	v_max_f32_e32 v81, 0, v81
	v_pk_mul_f32 v[90:91], v[82:83], v[82:83]
	v_pk_mul_f32 v[84:85], v[84:85], v[84:85]
	v_pk_mul_f32 v[88:89], v[80:81], v[80:81]
	v_max_f32_e32 v80, 0, v86
	v_max_f32_e32 v81, 0, v87
	v_pk_mul_f32 v[86:87], v[80:81], v[80:81]
	v_cvt_pk_bf16_f32 v242, v84, v85
	v_cvt_pk_bf16_f32 v243, v86, v87
	v_cvt_pk_bf16_f32 v244, v88, v89
	v_cvt_pk_bf16_f32 v245, v90, v91
	v_mov_b32_e32 v246, v238
	v_mov_b32_e32 v247, v239
	v_mov_b32_e32 v248, v240
	v_mov_b32_e32 v249, v241
	v_mov_b32_dpp v238, v242 row_shr:8 row_mask:0xf bank_mask:0xc
	v_mov_b32_dpp v239, v243 row_shr:8 row_mask:0xf bank_mask:0xc
	v_mov_b32_dpp v240, v244 row_shr:8 row_mask:0xf bank_mask:0xc
	v_mov_b32_dpp v241, v245 row_shr:8 row_mask:0xf bank_mask:0xc
	global_store_dwordx4 v[98:99], v[238:241], off
	v_lshl_add_u64 v[236:237], v[98:99], 0, vcc
	v_mov_b32_dpp v242, v246 row_shl:8 row_mask:0xf bank_mask:0x3
	v_mov_b32_dpp v243, v247 row_shl:8 row_mask:0xf bank_mask:0x3
	v_mov_b32_dpp v244, v248 row_shl:8 row_mask:0xf bank_mask:0x3
	v_mov_b32_dpp v245, v249 row_shl:8 row_mask:0xf bank_mask:0x3
	global_store_dwordx4 v[236:237], v[242:245], off
	s_nop 1
	v_mov_b32_e32 v80, v231
	v_pk_mul_f32 v[72:73], v[72:73], v[80:81] op_sel_hi:[1,0]
	v_pk_mul_f32 v[78:79], v[78:79], v[80:81] op_sel_hi:[1,0]
	v_pk_mul_f32 v[76:77], v[76:77], v[80:81] op_sel_hi:[1,0]
	v_pk_mul_f32 v[74:75], v[74:75], v[80:81] op_sel_hi:[1,0]
	v_max_f32_e32 v72, 0, v72
	v_max_f32_e32 v73, 0, v73
	v_lshlrev_b64 v[82:83], 13, v[164:165]
	v_max_f32_e32 v76, 0, v76
	v_max_f32_e32 v77, 0, v77
	v_pk_mul_f32 v[84:85], v[72:73], v[72:73]
	v_max_f32_e32 v72, 0, v78
	v_max_f32_e32 v74, 0, v74
	v_max_f32_e32 v73, 0, v79
	v_max_f32_e32 v75, 0, v75
	v_lshl_add_u64 v[82:83], s[96:97], 0, v[82:83]
	v_pk_mul_f32 v[76:77], v[76:77], v[76:77]
	v_pk_mul_f32 v[78:79], v[72:73], v[72:73]
	v_pk_mul_f32 v[86:87], v[74:75], v[74:75]
	v_pk_mul_f32 v[64:65], v[64:65], v[80:81] op_sel_hi:[1,0]
	v_lshl_add_u64 v[82:83], v[82:83], 0, v[148:149]
	v_cvt_pk_bf16_f32 v238, v76, v77
	v_cvt_pk_bf16_f32 v239, v78, v79
	v_cvt_pk_bf16_f32 v240, v84, v85
	v_cvt_pk_bf16_f32 v241, v86, v87
	v_pk_mul_f32 v[70:71], v[70:71], v[80:81] op_sel_hi:[1,0]
	v_max_f32_e32 v64, 0, v64
	v_max_f32_e32 v65, 0, v65
	v_pk_mul_f32 v[68:69], v[68:69], v[80:81] op_sel_hi:[1,0]
	v_pk_mul_f32 v[66:67], v[66:67], v[80:81] op_sel_hi:[1,0]
	v_pk_mul_f32 v[72:73], v[64:65], v[64:65]
	v_max_f32_e32 v64, 0, v70
	v_max_f32_e32 v65, 0, v71
	v_max_f32_e32 v68, 0, v68
	v_max_f32_e32 v69, 0, v69
	v_pk_mul_f32 v[68:69], v[68:69], v[68:69]
	v_pk_mul_f32 v[76:77], v[64:65], v[64:65]
	v_cvt_pk_bf16_f32 v242, v68, v69
	s_waitcnt lgkmcnt(0)
	v_max_f32_e32 v66, 0, v66
	v_max_f32_e32 v67, 0, v67
	v_pk_mul_f32 v[78:79], v[66:67], v[66:67]
	v_cvt_pk_bf16_f32 v243, v76, v77
	v_cvt_pk_bf16_f32 v244, v72, v73
	v_cvt_pk_bf16_f32 v245, v78, v79
	v_mov_b32_e32 v246, v238
	v_mov_b32_e32 v247, v239
	v_mov_b32_e32 v248, v240
	v_mov_b32_e32 v249, v241
	v_mov_b32_dpp v238, v242 row_shr:8 row_mask:0xf bank_mask:0xc
	v_mov_b32_dpp v239, v243 row_shr:8 row_mask:0xf bank_mask:0xc
	v_mov_b32_dpp v240, v244 row_shr:8 row_mask:0xf bank_mask:0xc
	v_mov_b32_dpp v241, v245 row_shr:8 row_mask:0xf bank_mask:0xc
	global_store_dwordx4 v[82:83], v[238:241], off
	v_lshl_add_u64 v[236:237], v[82:83], 0, vcc
	v_mov_b32_dpp v242, v246 row_shl:8 row_mask:0xf bank_mask:0x3
	v_mov_b32_dpp v243, v247 row_shl:8 row_mask:0xf bank_mask:0x3
	v_mov_b32_dpp v244, v248 row_shl:8 row_mask:0xf bank_mask:0x3
	v_mov_b32_dpp v245, v249 row_shl:8 row_mask:0xf bank_mask:0x3
	global_store_dwordx4 v[236:237], v[242:245], off
	s_waitcnt lgkmcnt(0)
; __device__ __forceinline__ unsigned pk2(float lo, float hi) { const f32x2 v = (f32x2){lo, hi}; const bf16x2_t b = __builtin_convertvector(v, bf16x2_t); return __builtin_bit_cast(unsigned, b); }
;     __device__ __forceinline__ void operator()(const f32x4 (&acc)[2][2][4][2], const Unit& u, int wr, int wc, int fr, int fq, const float (&)[8]) const {
;     ...
;             for (int m = 0; m < 4; ++m) { const int row = row0 + ai * HALF + m * 16; const float rs = rsqrtf(ep[ai * 4 + m] * (1.0f / 1024.0f) + EPS);
;                 u16* rowp = O + (size_t)row * ldc + col0;
; #pragma unroll
;                 for (int bj = 0; bj < 2; ++bj) { f32x4 v0 = acc[ai][bj][m][0] * rs, v1 = acc[ai][bj][m][1] * rs;
;                     if (ACT == 1) {
; #pragma unroll
;                         for (int j = 0; j < 4; ++j) { const float a0 = fmaxf(v0[j], 0.f), a1 = fmaxf(v1[j], 0.f); v0[j] = a0 * a0; v1[j] = a1 * a1; } }
;                     u32x4 w; w.x = pk2(v0[0], v0[1]); w.y = pk2(v0[2], v0[3]); w.z = pk2(v1[0], v1[1]); w.w = pk2(v1[2], v1[3]);
;                     *(u32x4*)(rowp + bj * HALF) = w; } }
	s_nop 0
	s_nop 0
	s_nop 0
	s_nop 1
	v_lshlrev_b64 v[66:67], 13, v[162:163]
	v_lshl_add_u64 v[66:67], s[96:97], 0, v[66:67]
	v_lshl_add_u64 v[66:67], v[66:67], 0, v[148:149]
	v_mov_b32_e32 v68, v232
	v_pk_mul_f32 v[56:57], v[56:57], v[68:69] op_sel_hi:[1,0]
	v_pk_mul_f32 v[62:63], v[62:63], v[68:69] op_sel_hi:[1,0]
	v_pk_mul_f32 v[60:61], v[60:61], v[68:69] op_sel_hi:[1,0]
	v_pk_mul_f32 v[58:59], v[58:59], v[68:69] op_sel_hi:[1,0]
	v_max_f32_e32 v56, 0, v56
	v_max_f32_e32 v57, 0, v57
	v_max_f32_e32 v60, 0, v60
	v_max_f32_e32 v61, 0, v61
	v_pk_mul_f32 v[70:71], v[56:57], v[56:57]
	v_max_f32_e32 v56, 0, v62
	v_max_f32_e32 v58, 0, v58
	v_max_f32_e32 v57, 0, v63
	v_max_f32_e32 v59, 0, v59
	v_pk_mul_f32 v[60:61], v[60:61], v[60:61]
	v_pk_mul_f32 v[62:63], v[56:57], v[56:57]
	v_pk_mul_f32 v[72:73], v[58:59], v[58:59]
	v_pk_mul_f32 v[50:51], v[50:51], v[68:69] op_sel_hi:[1,0]
	v_cvt_pk_bf16_f32 v238, v60, v61
	v_cvt_pk_bf16_f32 v239, v62, v63
	v_cvt_pk_bf16_f32 v240, v70, v71
	v_cvt_pk_bf16_f32 v241, v72, v73
	v_pk_mul_f32 v[52:53], v[52:53], v[68:69] op_sel_hi:[1,0]
	v_pk_mul_f32 v[48:49], v[48:49], v[68:69] op_sel_hi:[1,0]
	v_max_f32_e32 v50, 0, v50
	v_max_f32_e32 v51, 0, v51
	v_pk_mul_f32 v[54:55], v[54:55], v[68:69] op_sel_hi:[1,0]
	v_max_f32_e32 v52, 0, v52
	v_max_f32_e32 v48, 0, v48
	v_max_f32_e32 v53, 0, v53
	v_max_f32_e32 v49, 0, v49
	v_pk_mul_f32 v[58:59], v[50:51], v[50:51]
	v_pk_mul_f32 v[52:53], v[52:53], v[52:53]
	v_pk_mul_f32 v[56:57], v[48:49], v[48:49]
	v_max_f32_e32 v48, 0, v54
	v_max_f32_e32 v49, 0, v55
	v_pk_mul_f32 v[54:55], v[48:49], v[48:49]
	v_cvt_pk_bf16_f32 v242, v52, v53
	v_cvt_pk_bf16_f32 v243, v54, v55
	v_cvt_pk_bf16_f32 v244, v56, v57
	v_cvt_pk_bf16_f32 v245, v58, v59
	v_mov_b32_e32 v246, v238
	v_mov_b32_e32 v247, v239
	v_mov_b32_e32 v248, v240
	v_mov_b32_e32 v249, v241
	v_mov_b32_dpp v238, v242 row_shr:8 row_mask:0xf bank_mask:0xc
	v_mov_b32_dpp v239, v243 row_shr:8 row_mask:0xf bank_mask:0xc
	v_mov_b32_dpp v240, v244 row_shr:8 row_mask:0xf bank_mask:0xc
	v_mov_b32_dpp v241, v245 row_shr:8 row_mask:0xf bank_mask:0xc
	global_store_dwordx4 v[66:67], v[238:241], off
	v_lshl_add_u64 v[236:237], v[66:67], 0, vcc
	v_mov_b32_dpp v242, v246 row_shl:8 row_mask:0xf bank_mask:0x3
	v_mov_b32_dpp v243, v247 row_shl:8 row_mask:0xf bank_mask:0x3
	v_mov_b32_dpp v244, v248 row_shl:8 row_mask:0xf bank_mask:0x3
	v_mov_b32_dpp v245, v249 row_shl:8 row_mask:0xf bank_mask:0x3
	global_store_dwordx4 v[236:237], v[242:245], off
	s_nop 1
	v_mov_b32_e32 v48, v233
	v_pk_mul_f32 v[40:41], v[40:41], v[48:49] op_sel_hi:[1,0]
	v_pk_mul_f32 v[46:47], v[46:47], v[48:49] op_sel_hi:[1,0]
	v_pk_mul_f32 v[44:45], v[44:45], v[48:49] op_sel_hi:[1,0]
	v_pk_mul_f32 v[42:43], v[42:43], v[48:49] op_sel_hi:[1,0]
	v_max_f32_e32 v40, 0, v40
	v_max_f32_e32 v41, 0, v41
	v_lshlrev_b64 v[50:51], 13, v[156:157]
	v_max_f32_e32 v44, 0, v44
	v_max_f32_e32 v45, 0, v45
	v_pk_mul_f32 v[52:53], v[40:41], v[40:41]
	v_max_f32_e32 v40, 0, v46
	v_max_f32_e32 v42, 0, v42
	v_max_f32_e32 v41, 0, v47
	v_max_f32_e32 v43, 0, v43
	v_lshl_add_u64 v[50:51], s[96:97], 0, v[50:51]
	v_pk_mul_f32 v[44:45], v[44:45], v[44:45]
	v_pk_mul_f32 v[46:47], v[40:41], v[40:41]
	v_pk_mul_f32 v[54:55], v[42:43], v[42:43]
	v_pk_mul_f32 v[32:33], v[32:33], v[48:49] op_sel_hi:[1,0]
	v_lshl_add_u64 v[50:51], v[50:51], 0, v[148:149]
	v_cvt_pk_bf16_f32 v238, v44, v45
	v_cvt_pk_bf16_f32 v239, v46, v47
	v_cvt_pk_bf16_f32 v240, v52, v53
	v_cvt_pk_bf16_f32 v241, v54, v55
	v_pk_mul_f32 v[38:39], v[38:39], v[48:49] op_sel_hi:[1,0]
	v_max_f32_e32 v32, 0, v32
	v_max_f32_e32 v33, 0, v33
	v_pk_mul_f32 v[36:37], v[36:37], v[48:49] op_sel_hi:[1,0]
	v_pk_mul_f32 v[34:35], v[34:35], v[48:49] op_sel_hi:[1,0]
	v_pk_mul_f32 v[40:41], v[32:33], v[32:33]
	v_max_f32_e32 v32, 0, v38
	v_max_f32_e32 v33, 0, v39
	v_max_f32_e32 v36, 0, v36
	v_max_f32_e32 v37, 0, v37
	v_pk_mul_f32 v[36:37], v[36:37], v[36:37]
	v_pk_mul_f32 v[44:45], v[32:33], v[32:33]
	v_cvt_pk_bf16_f32 v242, v36, v37
	s_waitcnt lgkmcnt(0)
	v_max_f32_e32 v34, 0, v34
	v_max_f32_e32 v35, 0, v35
	v_pk_mul_f32 v[46:47], v[34:35], v[34:35]
	v_cvt_pk_bf16_f32 v243, v44, v45
	v_cvt_pk_bf16_f32 v244, v40, v41
	v_cvt_pk_bf16_f32 v245, v46, v47
	v_mov_b32_e32 v246, v238
	v_mov_b32_e32 v247, v239
	v_mov_b32_e32 v248, v240
	v_mov_b32_e32 v249, v241
	v_mov_b32_dpp v238, v242 row_shr:8 row_mask:0xf bank_mask:0xc
	v_mov_b32_dpp v239, v243 row_shr:8 row_mask:0xf bank_mask:0xc
	v_mov_b32_dpp v240, v244 row_shr:8 row_mask:0xf bank_mask:0xc
	v_mov_b32_dpp v241, v245 row_shr:8 row_mask:0xf bank_mask:0xc
	global_store_dwordx4 v[50:51], v[238:241], off
	v_lshl_add_u64 v[236:237], v[50:51], 0, vcc
	v_mov_b32_dpp v242, v246 row_shl:8 row_mask:0xf bank_mask:0x3
	v_mov_b32_dpp v243, v247 row_shl:8 row_mask:0xf bank_mask:0x3
	v_mov_b32_dpp v244, v248 row_shl:8 row_mask:0xf bank_mask:0x3
	v_mov_b32_dpp v245, v249 row_shl:8 row_mask:0xf bank_mask:0x3
	global_store_dwordx4 v[236:237], v[242:245], off
	s_waitcnt lgkmcnt(0)
; __device__ __forceinline__ unsigned pk2(float lo, float hi) { const f32x2 v = (f32x2){lo, hi}; const bf16x2_t b = __builtin_convertvector(v, bf16x2_t); return __builtin_bit_cast(unsigned, b); }
;     __device__ __forceinline__ void operator()(const f32x4 (&acc)[2][2][4][2], const Unit& u, int wr, int wc, int fr, int fq, const float (&)[8]) const {
;     ...
;             for (int m = 0; m < 4; ++m) { const int row = row0 + ai * HALF + m * 16; const float rs = rsqrtf(ep[ai * 4 + m] * (1.0f / 1024.0f) + EPS);
;                 u16* rowp = O + (size_t)row * ldc + col0;
; #pragma unroll
;                 for (int bj = 0; bj < 2; ++bj) { f32x4 v0 = acc[ai][bj][m][0] * rs, v1 = acc[ai][bj][m][1] * rs;
;                     if (ACT == 1) {
; #pragma unroll
;                         for (int j = 0; j < 4; ++j) { const float a0 = fmaxf(v0[j], 0.f), a1 = fmaxf(v1[j], 0.f); v0[j] = a0 * a0; v1[j] = a1 * a1; } }
;                     u32x4 w; w.x = pk2(v0[0], v0[1]); w.y = pk2(v0[2], v0[3]); w.z = pk2(v1[0], v1[1]); w.w = pk2(v1[2], v1[3]);
;                     *(u32x4*)(rowp + bj * HALF) = w; } }
; template <class Epi>
; __device__ __forceinline__ void gemm_phase(LAS unsigned char* lds, const Gemm g, const StaticOrder& S, const Epi& E) {
;     ...
;         E(acc, cur, wr, wc, fr, fq, epre);
;         if (!has_next) break;
	s_nop 0
	s_nop 0
	s_nop 0
	s_nop 1
	v_lshlrev_b64 v[34:35], 13, v[150:151]
	v_lshl_add_u64 v[34:35], s[96:97], 0, v[34:35]
	v_lshl_add_u64 v[34:35], v[34:35], 0, v[148:149]
	v_mov_b32_e32 v36, v234
	v_pk_mul_f32 v[24:25], v[24:25], v[36:37] op_sel_hi:[1,0]
	v_pk_mul_f32 v[30:31], v[30:31], v[36:37] op_sel_hi:[1,0]
	v_pk_mul_f32 v[28:29], v[28:29], v[36:37] op_sel_hi:[1,0]
	v_pk_mul_f32 v[26:27], v[26:27], v[36:37] op_sel_hi:[1,0]
	v_max_f32_e32 v24, 0, v24
	v_max_f32_e32 v25, 0, v25
	v_max_f32_e32 v28, 0, v28
	v_max_f32_e32 v29, 0, v29
	v_pk_mul_f32 v[38:39], v[24:25], v[24:25]
	v_max_f32_e32 v24, 0, v30
	v_max_f32_e32 v26, 0, v26
	v_max_f32_e32 v25, 0, v31
	v_max_f32_e32 v27, 0, v27
	v_pk_mul_f32 v[28:29], v[28:29], v[28:29]
	v_pk_mul_f32 v[30:31], v[24:25], v[24:25]
	v_pk_mul_f32 v[40:41], v[26:27], v[26:27]
	v_pk_mul_f32 v[18:19], v[18:19], v[36:37] op_sel_hi:[1,0]
	v_cvt_pk_bf16_f32 v238, v28, v29
	v_cvt_pk_bf16_f32 v239, v30, v31
	v_cvt_pk_bf16_f32 v240, v38, v39
	v_cvt_pk_bf16_f32 v241, v40, v41
	v_pk_mul_f32 v[20:21], v[20:21], v[36:37] op_sel_hi:[1,0]
	v_pk_mul_f32 v[16:17], v[16:17], v[36:37] op_sel_hi:[1,0]
	v_max_f32_e32 v18, 0, v18
	v_max_f32_e32 v19, 0, v19
	v_pk_mul_f32 v[22:23], v[22:23], v[36:37] op_sel_hi:[1,0]
	v_max_f32_e32 v20, 0, v20
	v_max_f32_e32 v16, 0, v16
	v_max_f32_e32 v21, 0, v21
	v_max_f32_e32 v17, 0, v17
	v_pk_mul_f32 v[26:27], v[18:19], v[18:19]
	v_pk_mul_f32 v[20:21], v[20:21], v[20:21]
	v_pk_mul_f32 v[24:25], v[16:17], v[16:17]
	v_max_f32_e32 v16, 0, v22
	v_max_f32_e32 v17, 0, v23
	v_pk_mul_f32 v[22:23], v[16:17], v[16:17]
	v_cvt_pk_bf16_f32 v242, v20, v21
	v_cvt_pk_bf16_f32 v243, v22, v23
	v_cvt_pk_bf16_f32 v244, v24, v25
	v_cvt_pk_bf16_f32 v245, v26, v27
	v_mov_b32_e32 v246, v238
	v_mov_b32_e32 v247, v239
	v_mov_b32_e32 v248, v240
	v_mov_b32_e32 v249, v241
	v_mov_b32_dpp v238, v242 row_shr:8 row_mask:0xf bank_mask:0xc
	v_mov_b32_dpp v239, v243 row_shr:8 row_mask:0xf bank_mask:0xc
	v_mov_b32_dpp v240, v244 row_shr:8 row_mask:0xf bank_mask:0xc
	v_mov_b32_dpp v241, v245 row_shr:8 row_mask:0xf bank_mask:0xc
	global_store_dwordx4 v[34:35], v[238:241], off
	v_lshl_add_u64 v[236:237], v[34:35], 0, vcc
	v_mov_b32_dpp v242, v246 row_shl:8 row_mask:0xf bank_mask:0x3
	v_mov_b32_dpp v243, v247 row_shl:8 row_mask:0xf bank_mask:0x3
	v_mov_b32_dpp v244, v248 row_shl:8 row_mask:0xf bank_mask:0x3
	v_mov_b32_dpp v245, v249 row_shl:8 row_mask:0xf bank_mask:0x3
	global_store_dwordx4 v[236:237], v[242:245], off
	s_nop 1
	v_mov_b32_e32 v16, v235
	v_pk_mul_f32 v[8:9], v[8:9], v[16:17] op_sel_hi:[1,0]
	v_pk_mul_f32 v[14:15], v[14:15], v[16:17] op_sel_hi:[1,0]
	v_pk_mul_f32 v[12:13], v[12:13], v[16:17] op_sel_hi:[1,0]
	v_pk_mul_f32 v[10:11], v[10:11], v[16:17] op_sel_hi:[1,0]
	v_max_f32_e32 v8, 0, v8
	v_max_f32_e32 v9, 0, v9
	v_lshlrev_b64 v[18:19], 13, v[146:147]
	v_max_f32_e32 v12, 0, v12
	v_max_f32_e32 v13, 0, v13
	v_pk_mul_f32 v[20:21], v[8:9], v[8:9]
	v_max_f32_e32 v8, 0, v14
	v_max_f32_e32 v10, 0, v10
	v_max_f32_e32 v9, 0, v15
	v_max_f32_e32 v11, 0, v11
	v_lshl_add_u64 v[18:19], s[96:97], 0, v[18:19]
	v_pk_mul_f32 v[12:13], v[12:13], v[12:13]
	v_pk_mul_f32 v[14:15], v[8:9], v[8:9]
	v_pk_mul_f32 v[22:23], v[10:11], v[10:11]
	v_pk_mul_f32 v[0:1], v[0:1], v[16:17] op_sel_hi:[1,0]
	v_lshl_add_u64 v[18:19], v[18:19], 0, v[148:149]
	v_cvt_pk_bf16_f32 v238, v12, v13
	v_cvt_pk_bf16_f32 v239, v14, v15
	v_cvt_pk_bf16_f32 v240, v20, v21
	v_cvt_pk_bf16_f32 v241, v22, v23
	v_pk_mul_f32 v[6:7], v[6:7], v[16:17] op_sel_hi:[1,0]
	v_pk_mul_f32 v[4:5], v[4:5], v[16:17] op_sel_hi:[1,0]
	v_pk_mul_f32 v[2:3], v[2:3], v[16:17] op_sel_hi:[1,0]
	v_max_f32_e32 v0, 0, v0
	v_max_f32_e32 v1, 0, v1
	v_max_f32_e32 v4, 0, v4
	v_max_f32_e32 v5, 0, v5
	v_pk_mul_f32 v[8:9], v[0:1], v[0:1]
	v_max_f32_e32 v0, 0, v6
	v_max_f32_e32 v2, 0, v2
	v_max_f32_e32 v1, 0, v7
	v_max_f32_e32 v3, 0, v3
	v_pk_mul_f32 v[4:5], v[4:5], v[4:5]
	v_pk_mul_f32 v[6:7], v[0:1], v[0:1]
	v_pk_mul_f32 v[10:11], v[2:3], v[2:3]
	v_cvt_pk_bf16_f32 v242, v4, v5
	v_cvt_pk_bf16_f32 v243, v6, v7
	v_cvt_pk_bf16_f32 v244, v8, v9
	v_cvt_pk_bf16_f32 v245, v10, v11
	v_mov_b32_e32 v246, v238
	v_mov_b32_e32 v247, v239
	v_mov_b32_e32 v248, v240
	v_mov_b32_e32 v249, v241
	v_mov_b32_dpp v238, v242 row_shr:8 row_mask:0xf bank_mask:0xc
	v_mov_b32_dpp v239, v243 row_shr:8 row_mask:0xf bank_mask:0xc
	v_mov_b32_dpp v240, v244 row_shr:8 row_mask:0xf bank_mask:0xc
	v_mov_b32_dpp v241, v245 row_shr:8 row_mask:0xf bank_mask:0xc
	global_store_dwordx4 v[18:19], v[238:241], off
	v_lshl_add_u64 v[236:237], v[18:19], 0, vcc
	v_mov_b32_dpp v242, v246 row_shl:8 row_mask:0xf bank_mask:0x3
	v_mov_b32_dpp v243, v247 row_shl:8 row_mask:0xf bank_mask:0x3
	v_mov_b32_dpp v244, v248 row_shl:8 row_mask:0xf bank_mask:0x3
	v_mov_b32_dpp v245, v249 row_shl:8 row_mask:0xf bank_mask:0x3
	global_store_dwordx4 v[236:237], v[242:245], off
	s_and_b64 vcc, exec, s[0:1]
	s_cbranch_vccz .LBB0_1197
	s_waitcnt vmcnt(0)
	s_cmpk_gt_u32 s7, 0xff
	s_cbranch_scc1 .LBB0_1208
	s_barrier
